# bf16-row GEMM: deferred epilogue split - ai=0 pieces ride in the tile's own last MFMA block (peeled last K-iteration), ai=1 pieces in the next tile's first block; epilogue state computed inside the fi
# speedup vs baseline: 1.0035x; 1.0019x over previous
.LBB0_395:
	s_ashr_i32 s75, s74, 31
	s_lshl_b64 s[28:29], s[74:75], 19
	s_add_u32 s76, s62, s28
	s_addc_u32 s77, s63, s29
	s_and_b64 s[28:29], s[8:9], exec
	s_cselect_b32 s11, s77, s13
	s_cselect_b32 s30, s76, s12
	s_ashr_i32 s73, s72, 31
	s_lshl_b64 s[28:29], s[72:73], 19
	s_add_u32 s78, s20, s28
	s_addc_u32 s79, s21, s29
	s_and_b64 s[28:29], s[8:9], exec
	s_cselect_b32 s31, s79, s15
	s_cselect_b32 s47, s78, s14
	s_add_u32 s12, s12, 0x40080
	s_addc_u32 s13, s13, 0
	s_add_u32 s54, s14, 0x100
	s_addc_u32 s55, s15, 0
	s_mov_b32 s73, -2
	s_cmp_lg_u32 s37, 0
	s_cbranch_scc1 .Lmy_b16_pdefer
	s_add_u32 s1, s12, 0xfffc0080
	s_addc_u32 s14, s13, -1
	s_add_i32 s33, 0, 0x10000
	s_cmp_eq_u32 s73, 12
	s_cselect_b32 s29, s11, s14
	s_cselect_b32 s28, s30, s1
	v_add_u32_e32 v100, s33, v154
	s_cselect_b32 s15, s31, s55
	s_cselect_b32 s14, s47, s54
	s_add_i32 s1, 0, 0x14000
	ds_read_b128 v[144:147], v100
	ds_read_b128 v[148:151], v100 offset:1024
	ds_read_b128 v[158:161], v100 offset:2048
	ds_read_b128 v[162:165], v100 offset:3072
	v_add_u32_e32 v100, s1, v154
	ds_read_b128 v[166:169], v100
	ds_read_b128 v[170:173], v100 offset:1024
	ds_read_b128 v[174:177], v100 offset:2048
	ds_read_b128 v[178:181], v100 offset:3072
	v_lshl_add_u64 v[152:153], s[12:13], 0, v[140:141]
	s_add_i32 m0, s41, 0xc000
	ds_read_b128 v[182:185], v156
	ds_read_b128 v[186:189], v156 offset:1024
	ds_read_b128 v[190:193], v156 offset:2048
	ds_read_b128 v[194:197], v156 offset:3072
	ds_read_b128 v[198:201], v156 offset:4096
	ds_read_b128 v[202:205], v156 offset:5120
	ds_read_b128 v[208:211], v156 offset:6144
	ds_read_b128 v[226:229], v156 offset:7168
	global_load_lds_dwordx4 v[152:153], off
	v_lshl_add_u64 v[152:153], s[12:13], 0, v[142:143]
	s_add_i32 m0, s41, 0xe000
	s_nop 0
	global_load_lds_dwordx4 v[152:153], off
	s_waitcnt vmcnt(24)
	s_waitcnt lgkmcnt(0)
	s_barrier
	s_setprio 1
	s_waitcnt lgkmcnt(0)
	v_mfma_f32_16x16x32_bf16 v[126:129], v[144:147], v[182:185], 0
	v_mfma_f32_16x16x32_bf16 v[122:125], v[158:161], v[182:185], 0
	v_mfma_f32_16x16x32_bf16 v[110:113], v[144:147], v[190:193], 0
	v_mfma_f32_16x16x32_bf16 v[106:109], v[158:161], v[190:193], 0
	v_mfma_f32_16x16x32_bf16 v[92:95], v[144:147], v[198:201], 0
	v_mfma_f32_16x16x32_bf16 v[88:91], v[158:161], v[198:201], 0
	v_mfma_f32_16x16x32_bf16 v[76:79], v[144:147], v[208:211], 0
	v_mfma_f32_16x16x32_bf16 v[72:75], v[158:161], v[208:211], 0
	v_mfma_f32_16x16x32_bf16 v[126:129], v[148:151], v[186:189], v[126:129]
	v_mfma_f32_16x16x32_bf16 v[122:125], v[162:165], v[186:189], v[122:125]
	v_mfma_f32_16x16x32_bf16 v[110:113], v[148:151], v[194:197], v[110:113]
	v_mfma_f32_16x16x32_bf16 v[106:109], v[162:165], v[194:197], v[106:109]
	v_mfma_f32_16x16x32_bf16 v[92:95], v[148:151], v[202:205], v[92:95]
	v_mfma_f32_16x16x32_bf16 v[88:91], v[162:165], v[202:205], v[88:91]
	v_mfma_f32_16x16x32_bf16 v[76:79], v[148:151], v[226:229], v[76:79]
	v_mfma_f32_16x16x32_bf16 v[72:75], v[162:165], v[226:229], v[72:75]
	s_setprio 0
	s_setprio 1
	v_mfma_f32_16x16x32_bf16 v[118:121], v[166:169], v[182:185], 0
	v_mfma_f32_16x16x32_bf16 v[114:117], v[174:177], v[182:185], 0
	v_mfma_f32_16x16x32_bf16 v[102:105], v[166:169], v[190:193], 0
	v_mfma_f32_16x16x32_bf16 v[96:99], v[174:177], v[190:193], 0
	v_mfma_f32_16x16x32_bf16 v[84:87], v[166:169], v[198:201], 0
	v_mfma_f32_16x16x32_bf16 v[80:83], v[174:177], v[198:201], 0
	v_mfma_f32_16x16x32_bf16 v[68:71], v[166:169], v[208:211], 0
	v_mfma_f32_16x16x32_bf16 v[64:67], v[174:177], v[208:211], 0
	v_mfma_f32_16x16x32_bf16 v[118:121], v[170:173], v[186:189], v[118:121]
	v_mfma_f32_16x16x32_bf16 v[114:117], v[178:181], v[186:189], v[114:117]
	v_mfma_f32_16x16x32_bf16 v[102:105], v[170:173], v[194:197], v[102:105]
	v_mfma_f32_16x16x32_bf16 v[96:99], v[178:181], v[194:197], v[96:99]
	v_mfma_f32_16x16x32_bf16 v[84:87], v[170:173], v[202:205], v[84:87]
	v_mfma_f32_16x16x32_bf16 v[80:83], v[178:181], v[202:205], v[80:83]
	v_mfma_f32_16x16x32_bf16 v[68:71], v[170:173], v[226:229], v[68:71]
	v_mfma_f32_16x16x32_bf16 v[64:67], v[178:181], v[226:229], v[64:67]
	s_setprio 0
	s_barrier
	s_add_i32 s33, s33, s34
	v_lshl_add_u64 v[152:153], s[14:15], 0, v[132:133]
	s_mov_b32 m0, s33
	ds_read_b128 v[182:185], v156 offset:16384
	ds_read_b128 v[186:189], v156 offset:17408
	ds_read_b128 v[190:193], v156 offset:18432
	ds_read_b128 v[194:197], v156 offset:19456
	ds_read_b128 v[198:201], v156 offset:20480
	ds_read_b128 v[202:205], v156 offset:21504
	ds_read_b128 v[208:211], v156 offset:22528
	ds_read_b128 v[226:229], v156 offset:23552
	global_load_lds_dwordx4 v[152:153], off
	s_add_i32 m0, s33, 0x2000
	s_add_u32 s80, s14, 0x40000
	v_lshl_add_u64 v[212:213], s[14:15], 0, v[136:137]
	s_addc_u32 s81, s15, 0
	s_add_i32 s1, s1, s34
	global_load_lds_dwordx4 v[212:213], off
	v_lshl_add_u64 v[230:231], s[80:81], 0, v[132:133]
	s_mov_b32 m0, s1
	v_lshl_add_u64 v[232:233], s[28:29], 0, v[134:135]
	global_load_lds_dwordx4 v[230:231], off
	v_lshl_add_u64 v[230:231], s[80:81], 0, v[136:137]
	s_add_i32 m0, s1, 0x2000
	s_nop 0
	global_load_lds_dwordx4 v[230:231], off
	v_lshl_add_u64 v[230:231], s[28:29], 0, v[130:131]
	s_mov_b32 m0, s41
	s_nop 0
	global_load_lds_dwordx4 v[230:231], off
	s_mov_b32 m0, s60
	s_nop 0
	global_load_lds_dwordx4 v[232:233], off
	s_lshl_b32 s46, s40, 8
	s_add_i32 s46, s46, s84
	v_or_b32_e32 v100, s46, v139
	v_lshlrev_b32_e32 v100, 2, v100
	global_load_dword v236, v100, s[66:67]
	global_load_dword v237, v100, s[66:67] offset:64
	global_load_dword v238, v100, s[66:67] offset:128
	global_load_dword v239, v100, s[66:67] offset:192
	global_load_dword v240, v100, s[66:67] offset:512
	global_load_dword v244, v100, s[66:67] offset:576
	global_load_dword v245, v100, s[66:67] offset:640
	global_load_dword v246, v100, s[66:67] offset:704
	s_lshl_b32 s100, s10, 8
	s_cmp_lt_i32 s100, s49
	s_cselect_b32 s36, s25, 1.0
	s_mov_b32 s101, 0
	s_mov_b64 vcc, s[22:23]
	s_mov_b32 s46, s100
	s_and_b64 s[2:3], s[50:51], exec
	s_cbranch_scc0 .Lmy_st_nosplit_fb
	s_mul_hi_u32 s101, s100, s52
	s_mul_i32 s75, s101, s35
	s_sub_i32 s46, s100, s75
	s_add_i32 s75, s101, 1
	s_sub_i32 s2, s46, s35
	s_cmp_ge_u32 s46, s35
	s_cselect_b32 s101, s75, s101
	s_cselect_b32 s46, s2, s46
	s_add_i32 s75, s101, 1
	s_cmp_ge_u32 s46, s35
	s_cselect_b32 s101, s75, s101
	s_mul_hi_i32 s3, s4, s101
	s_mul_i32 s2, s4, s101
	s_lshl_b64 s[2:3], s[2:3], 1
	s_add_u32 vcc_lo, s22, s2
	s_addc_u32 vcc_hi, s23, s3
	s_mul_i32 s75, s101, s35
	s_sub_i32 s46, s100, s75
.Lmy_st_nosplit_fb:
	s_cmp_lt_i32 s101, 2
	s_cselect_b64 s[2:3], -1, 0
	s_and_b64 s[2:3], s[2:3], s[64:65]
	s_orn2_b64 s[2:3], s[2:3], s[8:9]
	s_and_b64 s[2:3], s[2:3], exec
	s_cselect_b32 s82, 0, 1
	s_cselect_b32 s97, 13, 11
	s_lshl_b32 s75, s40, 8
	s_add_i32 s75, s75, s84
	s_and_b64 s[2:3], s[58:59], exec
	s_cbranch_scc0 .Lmy_st_plain_fb
	s_lshr_b32 s100, s46, 11
	s_lshl_b32 s101, s100, 1
	s_lshr_b32 s2, s75, 13
	s_mul_i32 s2, s2, 3
	s_add_i32 s2, s2, s100
	s_mov_b32 s3, 0
	s_lshl_b64 s[2:3], s[2:3], 25
	s_add_u32 s2, s22, s2
	s_addc_u32 s3, s23, s3
	s_lshl_b32 s0, s46, 14
	s_and_b32 s0, s0, 0x1e00000
	s_add_u32 s2, s2, s0
	s_addc_u32 s3, s3, 0
	s_lshl_b32 s0, s85, 1
	s_add_u32 s2, s2, s0
	s_addc_u32 s3, s3, 0
	s_and_b32 s0, s75, 0x1fff
	s_lshr_b32 s0, s0, s101
	s_lshl_b32 s0, s0, 8
	s_add_u32 s2, s2, s0
	s_addc_u32 s3, s3, 0
	s_lshr_b32 s0, 0x1000, s101
	s_lshr_b32 s100, 0x8000, s101
	s_mov_b32 s32, 0x200000
	s_lshl_b32 s46, 1, s101
	s_add_i32 s46, s46, -1
	s_sub_i32 s75, 13, s101
	v_lshrrev_b32_e32 v234, 2, v224
	v_and_b32_e32 v247, s46, v234
	v_lshlrev_b32_e32 v247, s75, v247
	v_lshrrev_b32_e32 v235, s101, v234
	v_add_lshl_u32 v247, v247, v235, 8
	v_and_b32_e32 v235, 3, v224
	v_lshl_add_u32 v247, v235, 4, v247
	s_branch .Lmy_st_done_fb
.Lmy_st_plain_fb:
	s_cmp_lt_i32 s75, s57
	s_cselect_b64 s[2:3], -1, 0
	s_or_b64 s[2:3], s[2:3], s[16:17]
	s_and_b64 s[2:3], s[2:3], exec
	s_cselect_b32 s100, vcc_lo, s18
	s_cselect_b32 s101, vcc_hi, s19
	s_cselect_b32 s0, 0, s57
	s_sub_i32 s75, s75, s0
	s_mul_hi_u32 s3, s75, s24
	s_mul_i32 s2, s75, s24
	s_add_i32 s0, s46, s85
	s_add_u32 s2, s2, s0
	s_addc_u32 s3, s3, 0
	s_lshl_b64 s[2:3], s[2:3], 1
	s_add_u32 s2, s2, s100
	s_addc_u32 s3, s3, s101
	s_lshl_b32 s0, s24, 5
	s_lshl_b32 s100, s24, 8
	s_movk_i32 s32, 0x100
	v_lshrrev_b32_e32 v234, 2, v224
	v_mul_lo_u32 v247, v234, s24
	v_and_b32_e32 v235, 3, v224
	v_lshlrev_b32_e32 v235, 3, v235
	v_add_lshl_u32 v247, v247, v235, 1
.Lmy_st_done_fb:
	s_add_u32 s90, s2, s100
	s_addc_u32 s91, s3, 0
	s_waitcnt vmcnt(32)
	s_waitcnt lgkmcnt(0)
	s_barrier
	s_setprio 1
	s_waitcnt lgkmcnt(0)
	v_mfma_f32_16x16x32_bf16 v[60:63], v[144:147], v[182:185], 0
	v_mfma_f32_16x16x32_bf16 v[56:59], v[158:161], v[182:185], 0
	v_mfma_f32_16x16x32_bf16 v[44:47], v[144:147], v[190:193], 0
	v_mfma_f32_16x16x32_bf16 v[40:43], v[158:161], v[190:193], 0
	v_mfma_f32_16x16x32_bf16 v[28:31], v[144:147], v[198:201], 0
	v_mfma_f32_16x16x32_bf16 v[24:27], v[158:161], v[198:201], 0
	v_mfma_f32_16x16x32_bf16 v[12:15], v[144:147], v[208:211], 0
	v_mfma_f32_16x16x32_bf16 v[8:11], v[158:161], v[208:211], 0
	v_mfma_f32_16x16x32_bf16 v[60:63], v[148:151], v[186:189], v[60:63]
	v_mfma_f32_16x16x32_bf16 v[56:59], v[162:165], v[186:189], v[56:59]
	v_mfma_f32_16x16x32_bf16 v[44:47], v[148:151], v[194:197], v[44:47]
	v_mfma_f32_16x16x32_bf16 v[40:43], v[162:165], v[194:197], v[40:43]
	v_mfma_f32_16x16x32_bf16 v[28:31], v[148:151], v[202:205], v[28:31]
	v_mfma_f32_16x16x32_bf16 v[24:27], v[162:165], v[202:205], v[24:27]
	v_mfma_f32_16x16x32_bf16 v[12:15], v[148:151], v[226:229], v[12:15]
	v_mfma_f32_16x16x32_bf16 v[8:11], v[162:165], v[226:229], v[8:11]
	s_setprio 0
	s_setprio 1
	v_mfma_f32_16x16x32_bf16 v[52:55], v[166:169], v[182:185], 0
	v_mfma_f32_16x16x32_bf16 v[48:51], v[174:177], v[182:185], 0
	v_mfma_f32_16x16x32_bf16 v[36:39], v[166:169], v[190:193], 0
	v_mfma_f32_16x16x32_bf16 v[32:35], v[174:177], v[190:193], 0
	v_mfma_f32_16x16x32_bf16 v[20:23], v[166:169], v[198:201], 0
	v_mfma_f32_16x16x32_bf16 v[16:19], v[174:177], v[198:201], 0
	v_mfma_f32_16x16x32_bf16 v[4:7], v[166:169], v[208:211], 0
	v_mfma_f32_16x16x32_bf16 v[0:3], v[174:177], v[208:211], 0
	v_mfma_f32_16x16x32_bf16 v[52:55], v[170:173], v[186:189], v[52:55]
	v_mfma_f32_16x16x32_bf16 v[48:51], v[178:181], v[186:189], v[48:51]
	v_mfma_f32_16x16x32_bf16 v[36:39], v[170:173], v[194:197], v[36:39]
	v_mfma_f32_16x16x32_bf16 v[32:35], v[178:181], v[194:197], v[32:35]
	v_mfma_f32_16x16x32_bf16 v[20:23], v[170:173], v[202:205], v[20:23]
	v_mfma_f32_16x16x32_bf16 v[16:19], v[178:181], v[202:205], v[16:19]
	v_mfma_f32_16x16x32_bf16 v[4:7], v[170:173], v[226:229], v[4:7]
	v_mfma_f32_16x16x32_bf16 v[0:3], v[178:181], v[226:229], v[0:3]
	s_setprio 0
	s_barrier
	s_add_i32 s1, 0, 0x18000
	v_add_u32_e32 v100, s1, v154
	s_add_i32 s33, 0, 0x1c000
	ds_read_b128 v[144:147], v100
	ds_read_b128 v[148:151], v100 offset:1024
	ds_read_b128 v[158:161], v100 offset:2048
	ds_read_b128 v[162:165], v100 offset:3072
	v_add_u32_e32 v100, s33, v154
	ds_read_b128 v[166:169], v100
	ds_read_b128 v[170:173], v100 offset:1024
	ds_read_b128 v[174:177], v100 offset:2048
	ds_read_b128 v[178:181], v100 offset:3072
	s_add_u32 s28, s28, 0x40000
	s_addc_u32 s29, s29, 0
	s_mov_b32 m0, s61
	v_lshl_add_u64 v[234:235], s[28:29], 0, v[130:131]
	ds_read_b128 v[182:185], v156 offset:32768
	ds_read_b128 v[186:189], v156 offset:33792
	ds_read_b128 v[190:193], v156 offset:34816
	ds_read_b128 v[194:197], v156 offset:35840
	ds_read_b128 v[198:201], v156 offset:36864
	ds_read_b128 v[202:205], v156 offset:37888
	ds_read_b128 v[208:211], v156 offset:38912
	ds_read_b128 v[226:229], v156 offset:39936
	global_load_lds_dwordx4 v[234:235], off
	v_lshl_add_u64 v[234:235], s[28:29], 0, v[134:135]
	s_mov_b32 m0, s69
	s_nop 0
	global_load_lds_dwordx4 v[234:235], off
	s_waitcnt vmcnt(16)
	s_waitcnt lgkmcnt(0)
	s_barrier
	s_setprio 1
	s_waitcnt lgkmcnt(0)
	v_mfma_f32_16x16x32_bf16 v[126:129], v[144:147], v[182:185], v[126:129]
	v_mfma_f32_16x16x32_bf16 v[122:125], v[158:161], v[182:185], v[122:125]
	v_mfma_f32_16x16x32_bf16 v[110:113], v[144:147], v[190:193], v[110:113]
	v_mfma_f32_16x16x32_bf16 v[106:109], v[158:161], v[190:193], v[106:109]
	v_mfma_f32_16x16x32_bf16 v[92:95], v[144:147], v[198:201], v[92:95]
	v_mfma_f32_16x16x32_bf16 v[88:91], v[158:161], v[198:201], v[88:91]
	v_mfma_f32_16x16x32_bf16 v[76:79], v[144:147], v[208:211], v[76:79]
	v_mfma_f32_16x16x32_bf16 v[72:75], v[158:161], v[208:211], v[72:75]
	v_mfma_f32_16x16x32_bf16 v[126:129], v[148:151], v[186:189], v[126:129]
	v_mfma_f32_16x16x32_bf16 v[122:125], v[162:165], v[186:189], v[122:125]
	v_mfma_f32_16x16x32_bf16 v[110:113], v[148:151], v[194:197], v[110:113]
	v_mfma_f32_16x16x32_bf16 v[106:109], v[162:165], v[194:197], v[106:109]
	v_mfma_f32_16x16x32_bf16 v[92:95], v[148:151], v[202:205], v[92:95]
	v_mfma_f32_16x16x32_bf16 v[88:91], v[162:165], v[202:205], v[88:91]
	v_mfma_f32_16x16x32_bf16 v[76:79], v[148:151], v[226:229], v[76:79]
	v_mfma_f32_16x16x32_bf16 v[72:75], v[162:165], v[226:229], v[72:75]
	s_setprio 0
	s_setprio 1
	v_mfma_f32_16x16x32_bf16 v[118:121], v[166:169], v[182:185], v[118:121]
	v_mfma_f32_16x16x32_bf16 v[114:117], v[174:177], v[182:185], v[114:117]
	v_mfma_f32_16x16x32_bf16 v[102:105], v[166:169], v[190:193], v[102:105]
	v_mfma_f32_16x16x32_bf16 v[96:99], v[174:177], v[190:193], v[96:99]
	v_mfma_f32_16x16x32_bf16 v[84:87], v[166:169], v[198:201], v[84:87]
	v_mfma_f32_16x16x32_bf16 v[80:83], v[174:177], v[198:201], v[80:83]
	v_mfma_f32_16x16x32_bf16 v[68:71], v[166:169], v[208:211], v[68:71]
	v_mfma_f32_16x16x32_bf16 v[64:67], v[174:177], v[208:211], v[64:67]
	v_mfma_f32_16x16x32_bf16 v[118:121], v[170:173], v[186:189], v[118:121]
	v_mfma_f32_16x16x32_bf16 v[114:117], v[178:181], v[186:189], v[114:117]
	v_mfma_f32_16x16x32_bf16 v[102:105], v[170:173], v[194:197], v[102:105]
	v_mfma_f32_16x16x32_bf16 v[96:99], v[178:181], v[194:197], v[96:99]
	v_mfma_f32_16x16x32_bf16 v[84:87], v[170:173], v[202:205], v[84:87]
	v_mfma_f32_16x16x32_bf16 v[80:83], v[178:181], v[202:205], v[80:83]
	v_mfma_f32_16x16x32_bf16 v[68:71], v[170:173], v[226:229], v[68:71]
	v_mfma_f32_16x16x32_bf16 v[64:67], v[178:181], v[226:229], v[64:67]
	s_setprio 0
	s_barrier
	s_add_i32 s1, s1, s34
	v_lshl_add_u64 v[152:153], v[152:153], 0, s[86:87]
	s_mov_b32 m0, s1
	ds_read_b128 v[182:185], v156 offset:49152
	ds_read_b128 v[186:189], v156 offset:50176
	ds_read_b128 v[190:193], v156 offset:51200
	ds_read_b128 v[194:197], v156 offset:52224
	ds_read_b128 v[198:201], v156 offset:53248
	ds_read_b128 v[202:205], v156 offset:54272
	ds_read_b128 v[208:211], v156 offset:55296
	ds_read_b128 v[226:229], v156 offset:56320
	global_load_lds_dwordx4 v[152:153], off
	s_add_i32 m0, s1, 0x2000
	s_add_u32 s14, s14, 0x40080
	v_lshl_add_u64 v[152:153], v[212:213], 0, s[86:87]
	s_addc_u32 s15, s15, 0
	s_add_i32 s1, s33, s34
	global_load_lds_dwordx4 v[152:153], off
	v_lshl_add_u64 v[152:153], s[14:15], 0, v[132:133]
	s_mov_b32 m0, s1
	s_nop 0
	global_load_lds_dwordx4 v[152:153], off
	v_lshl_add_u64 v[152:153], s[14:15], 0, v[136:137]
	s_add_i32 m0, s1, 0x2000
	s_nop 0
	global_load_lds_dwordx4 v[152:153], off
	v_lshl_add_u64 v[152:153], v[230:231], 0, s[86:87]
	s_mov_b32 m0, s89
	s_nop 0
	global_load_lds_dwordx4 v[152:153], off
	v_lshl_add_u64 v[152:153], v[232:233], 0, s[86:87]
	s_mov_b32 m0, s92
	s_nop 0
	global_load_lds_dwordx4 v[152:153], off
	s_waitcnt vmcnt(16)
	s_waitcnt lgkmcnt(0)
	s_barrier
	s_setprio 1
	s_waitcnt lgkmcnt(0)
	v_mfma_f32_16x16x32_bf16 v[60:63], v[144:147], v[182:185], v[60:63]
	v_mfma_f32_16x16x32_bf16 v[56:59], v[158:161], v[182:185], v[56:59]
	v_mfma_f32_16x16x32_bf16 v[44:47], v[144:147], v[190:193], v[44:47]
	v_mfma_f32_16x16x32_bf16 v[40:43], v[158:161], v[190:193], v[40:43]
	v_mfma_f32_16x16x32_bf16 v[28:31], v[144:147], v[198:201], v[28:31]
	v_mfma_f32_16x16x32_bf16 v[24:27], v[158:161], v[198:201], v[24:27]
	v_mfma_f32_16x16x32_bf16 v[12:15], v[144:147], v[208:211], v[12:15]
	v_mfma_f32_16x16x32_bf16 v[8:11], v[158:161], v[208:211], v[8:11]
	v_mfma_f32_16x16x32_bf16 v[60:63], v[148:151], v[186:189], v[60:63]
	v_mfma_f32_16x16x32_bf16 v[56:59], v[162:165], v[186:189], v[56:59]
	v_mfma_f32_16x16x32_bf16 v[44:47], v[148:151], v[194:197], v[44:47]
	v_mfma_f32_16x16x32_bf16 v[40:43], v[162:165], v[194:197], v[40:43]
	v_mfma_f32_16x16x32_bf16 v[28:31], v[148:151], v[202:205], v[28:31]
	v_mfma_f32_16x16x32_bf16 v[24:27], v[162:165], v[202:205], v[24:27]
	v_mfma_f32_16x16x32_bf16 v[12:15], v[148:151], v[226:229], v[12:15]
	v_mfma_f32_16x16x32_bf16 v[8:11], v[162:165], v[226:229], v[8:11]
	s_setprio 0
	s_setprio 1
	v_mfma_f32_16x16x32_bf16 v[52:55], v[166:169], v[182:185], v[52:55]
	v_mfma_f32_16x16x32_bf16 v[48:51], v[174:177], v[182:185], v[48:51]
	v_mfma_f32_16x16x32_bf16 v[36:39], v[166:169], v[190:193], v[36:39]
	v_mfma_f32_16x16x32_bf16 v[32:35], v[174:177], v[190:193], v[32:35]
	v_mfma_f32_16x16x32_bf16 v[20:23], v[166:169], v[198:201], v[20:23]
	v_mfma_f32_16x16x32_bf16 v[16:19], v[174:177], v[198:201], v[16:19]
	v_mfma_f32_16x16x32_bf16 v[4:7], v[166:169], v[208:211], v[4:7]
	v_mfma_f32_16x16x32_bf16 v[0:3], v[174:177], v[208:211], v[0:3]
	v_mfma_f32_16x16x32_bf16 v[52:55], v[170:173], v[186:189], v[52:55]
	v_mfma_f32_16x16x32_bf16 v[48:51], v[178:181], v[186:189], v[48:51]
	v_mfma_f32_16x16x32_bf16 v[36:39], v[170:173], v[194:197], v[36:39]
	v_mfma_f32_16x16x32_bf16 v[32:35], v[178:181], v[194:197], v[32:35]
	v_mfma_f32_16x16x32_bf16 v[20:23], v[170:173], v[202:205], v[20:23]
	v_mfma_f32_16x16x32_bf16 v[16:19], v[178:181], v[202:205], v[16:19]
	v_mfma_f32_16x16x32_bf16 v[4:7], v[170:173], v[226:229], v[4:7]
	v_mfma_f32_16x16x32_bf16 v[0:3], v[178:181], v[226:229], v[0:3]
	s_setprio 0
	s_barrier
	s_add_i32 s73, s73, 2
	s_add_u32 s12, s12, 0x100
	s_addc_u32 s13, s13, 0
	s_add_u32 s54, s54, 0x100
	s_addc_u32 s55, s55, 0
	s_branch .LBB0_396
.Lmy_b16_pdefer:
	s_add_u32 s1, s12, 0xfffc0080
	s_addc_u32 s14, s13, -1
	s_add_i32 s33, 0, 0x10000
	s_cmp_eq_u32 s73, 12
	s_cselect_b32 s29, s11, s14
	s_cselect_b32 s28, s30, s1
	v_add_u32_e32 v100, s33, v154
	s_cselect_b32 s15, s31, s55
	s_cselect_b32 s14, s47, s54
	s_add_i32 s1, 0, 0x14000
	ds_read_b128 v[144:147], v100
	ds_read_b128 v[148:151], v100 offset:1024
	ds_read_b128 v[158:161], v100 offset:2048
	ds_read_b128 v[162:165], v100 offset:3072
	v_add_u32_e32 v100, s1, v154
	ds_read_b128 v[166:169], v100
	ds_read_b128 v[170:173], v100 offset:1024
	ds_read_b128 v[174:177], v100 offset:2048
	ds_read_b128 v[178:181], v100 offset:3072
	v_lshl_add_u64 v[152:153], s[12:13], 0, v[140:141]
	s_add_i32 m0, s41, 0xc000
	ds_read_b128 v[182:185], v156
	ds_read_b128 v[186:189], v156 offset:1024
	ds_read_b128 v[190:193], v156 offset:2048
	ds_read_b128 v[194:197], v156 offset:3072
	ds_read_b128 v[198:201], v156 offset:4096
	ds_read_b128 v[202:205], v156 offset:5120
	ds_read_b128 v[208:211], v156 offset:6144
	ds_read_b128 v[226:229], v156 offset:7168
	global_load_lds_dwordx4 v[152:153], off
	v_lshl_add_u64 v[152:153], s[12:13], 0, v[142:143]
	s_add_i32 m0, s41, 0xe000
	s_nop 0
	global_load_lds_dwordx4 v[152:153], off
	s_waitcnt vmcnt(16)
	s_waitcnt lgkmcnt(0)
	s_barrier
	s_setprio 1
	s_waitcnt lgkmcnt(0)
	v_mfma_f32_16x16x32_bf16 v[126:129], v[144:147], v[182:185], 0
	v_and_b32_e32 v100, 3, v224
	v_lshlrev_b32_e32 v100, 6, v100
	v_and_or_b32 v100, v224, 60, v100
	v_mov_b32_e32 v152, v247
	v_fmamk_f32 v234, v240, 0x3a800000, v207
	v_mfma_f32_16x16x32_bf16 v[122:125], v[158:161], v[182:185], 0
	v_rsq_f32_e32 v234, v234
	s_nop 0
	v_mul_f32_e32 v234, s36, v234
	v_mul_f32_e32 v60, v234, v60
	v_mul_f32_e32 v61, v234, v61
	v_mul_f32_e32 v62, v234, v62
	v_mfma_f32_16x16x32_bf16 v[110:113], v[144:147], v[190:193], 0
	v_mul_f32_e32 v63, v234, v63
	v_mul_f32_e32 v56, v234, v56
	v_mul_f32_e32 v57, v234, v57
	v_mul_f32_e32 v58, v234, v58
	v_mul_f32_e32 v59, v234, v59
	v_cvt_pk_bf16_f32 v60, v60, v61
	v_mfma_f32_16x16x32_bf16 v[106:109], v[158:161], v[190:193], 0
	v_cvt_pk_bf16_f32 v61, v62, v63
	v_cvt_pk_bf16_f32 v62, v56, v57
	v_cvt_pk_bf16_f32 v63, v58, v59
	ds_bpermute_b32 v56, v100, v60
	ds_bpermute_b32 v57, v100, v61
	ds_bpermute_b32 v58, v100, v62
	v_mfma_f32_16x16x32_bf16 v[92:95], v[144:147], v[198:201], 0
	ds_bpermute_b32 v59, v100, v63
	v_fmamk_f32 v234, v244, 0x3a800000, v207
	v_rsq_f32_e32 v234, v234
	s_nop 0
	v_mul_f32_e32 v234, s36, v234
	v_mul_f32_e32 v44, v234, v44
	v_mfma_f32_16x16x32_bf16 v[88:91], v[158:161], v[198:201], 0
	v_mul_f32_e32 v45, v234, v45
	v_mul_f32_e32 v46, v234, v46
	v_mul_f32_e32 v47, v234, v47
	v_mul_f32_e32 v40, v234, v40
	v_mul_f32_e32 v41, v234, v41
	v_mul_f32_e32 v42, v234, v42
	v_mfma_f32_16x16x32_bf16 v[76:79], v[144:147], v[208:211], 0
	v_mul_f32_e32 v43, v234, v43
	v_cvt_pk_bf16_f32 v44, v44, v45
	v_cvt_pk_bf16_f32 v45, v46, v47
	v_cvt_pk_bf16_f32 v46, v40, v41
	v_cvt_pk_bf16_f32 v47, v42, v43
	ds_bpermute_b32 v40, v100, v44
	v_mfma_f32_16x16x32_bf16 v[72:75], v[158:161], v[208:211], 0
	ds_bpermute_b32 v41, v100, v45
	ds_bpermute_b32 v42, v100, v46
	ds_bpermute_b32 v43, v100, v47
	s_waitcnt lgkmcnt(4)
	global_store_dwordx4 v152, v[56:59], s[90:91] nt
	v_add_u32_e32 v152, s0, v152
	v_mfma_f32_16x16x32_bf16 v[126:129], v[148:151], v[186:189], v[126:129]
	v_fmamk_f32 v234, v245, 0x3a800000, v207
	v_rsq_f32_e32 v234, v234
	s_nop 0
	v_mul_f32_e32 v234, s36, v234
	v_mul_f32_e32 v28, v234, v28
	v_mul_f32_e32 v29, v234, v29
	v_mfma_f32_16x16x32_bf16 v[122:125], v[162:165], v[186:189], v[122:125]
	v_mul_f32_e32 v30, v234, v30
	v_mul_f32_e32 v31, v234, v31
	v_mul_f32_e32 v24, v234, v24
	v_mul_f32_e32 v25, v234, v25
	v_mul_f32_e32 v26, v234, v26
	v_mul_f32_e32 v27, v234, v27
	v_mfma_f32_16x16x32_bf16 v[110:113], v[148:151], v[194:197], v[110:113]
	v_cvt_pk_bf16_f32 v28, v28, v29
	v_cvt_pk_bf16_f32 v29, v30, v31
	v_cvt_pk_bf16_f32 v30, v24, v25
	v_cvt_pk_bf16_f32 v31, v26, v27
	ds_bpermute_b32 v24, v100, v28
	ds_bpermute_b32 v25, v100, v29
	v_mfma_f32_16x16x32_bf16 v[106:109], v[162:165], v[194:197], v[106:109]
	ds_bpermute_b32 v26, v100, v30
	ds_bpermute_b32 v27, v100, v31
	s_waitcnt lgkmcnt(4)
	global_store_dwordx4 v152, v[40:43], s[90:91] nt
	v_add_u32_e32 v152, s0, v152
	v_fmamk_f32 v234, v246, 0x3a800000, v207
	v_mfma_f32_16x16x32_bf16 v[92:95], v[148:151], v[202:205], v[92:95]
	v_rsq_f32_e32 v234, v234
	s_nop 0
	v_mul_f32_e32 v234, s36, v234
	v_mul_f32_e32 v12, v234, v12
	v_mul_f32_e32 v13, v234, v13
	v_mul_f32_e32 v14, v234, v14
	v_mfma_f32_16x16x32_bf16 v[88:91], v[162:165], v[202:205], v[88:91]
	v_mul_f32_e32 v15, v234, v15
	v_mul_f32_e32 v8, v234, v8
	v_mul_f32_e32 v9, v234, v9
	v_mul_f32_e32 v10, v234, v10
	v_mul_f32_e32 v11, v234, v11
	v_cvt_pk_bf16_f32 v12, v12, v13
	v_mfma_f32_16x16x32_bf16 v[76:79], v[148:151], v[226:229], v[76:79]
	v_cvt_pk_bf16_f32 v13, v14, v15
	v_cvt_pk_bf16_f32 v14, v8, v9
	v_cvt_pk_bf16_f32 v15, v10, v11
	ds_bpermute_b32 v8, v100, v12
	ds_bpermute_b32 v9, v100, v13
	ds_bpermute_b32 v10, v100, v14
	v_mfma_f32_16x16x32_bf16 v[72:75], v[162:165], v[226:229], v[72:75]
	ds_bpermute_b32 v11, v100, v15
	s_waitcnt lgkmcnt(4)
	global_store_dwordx4 v152, v[24:27], s[90:91] nt
	v_add_u32_e32 v152, s0, v152
	s_waitcnt lgkmcnt(0)
	global_store_dwordx4 v152, v[8:11], s[90:91] nt
	s_setprio 0
	s_setprio 1
	v_mfma_f32_16x16x32_bf16 v[118:121], v[166:169], v[182:185], 0
	v_add_u32_e32 v153, s32, v247
	v_fmamk_f32 v230, v240, 0x3a800000, v207
	v_rsq_f32_e32 v230, v230
	s_nop 0
	v_mul_f32_e32 v230, s36, v230
	v_mfma_f32_16x16x32_bf16 v[114:117], v[174:177], v[182:185], 0
	v_mul_f32_e32 v52, v230, v52
	v_mul_f32_e32 v53, v230, v53
	v_mul_f32_e32 v54, v230, v54
	v_mul_f32_e32 v55, v230, v55
	v_mul_f32_e32 v48, v230, v48
	v_mul_f32_e32 v49, v230, v49
	v_mfma_f32_16x16x32_bf16 v[102:105], v[166:169], v[190:193], 0
	v_mul_f32_e32 v50, v230, v50
	v_mul_f32_e32 v51, v230, v51
	v_cvt_pk_bf16_f32 v52, v52, v53
	v_cvt_pk_bf16_f32 v53, v54, v55
	v_cvt_pk_bf16_f32 v54, v48, v49
	v_cvt_pk_bf16_f32 v55, v50, v51
	v_mfma_f32_16x16x32_bf16 v[96:99], v[174:177], v[190:193], 0
	ds_bpermute_b32 v48, v100, v52
	ds_bpermute_b32 v49, v100, v53
	ds_bpermute_b32 v50, v100, v54
	ds_bpermute_b32 v51, v100, v55
	v_fmamk_f32 v230, v244, 0x3a800000, v207
	v_rsq_f32_e32 v230, v230
	v_mfma_f32_16x16x32_bf16 v[84:87], v[166:169], v[198:201], 0
	s_nop 0
	v_mul_f32_e32 v230, s36, v230
	v_mul_f32_e32 v36, v230, v36
	v_mul_f32_e32 v37, v230, v37
	v_mul_f32_e32 v38, v230, v38
	v_mfma_f32_16x16x32_bf16 v[80:83], v[174:177], v[198:201], 0
	v_mul_f32_e32 v39, v230, v39
	v_mul_f32_e32 v32, v230, v32
	v_mul_f32_e32 v33, v230, v33
	v_mul_f32_e32 v34, v230, v34
	v_mul_f32_e32 v35, v230, v35
	v_cvt_pk_bf16_f32 v36, v36, v37
	v_mfma_f32_16x16x32_bf16 v[68:71], v[166:169], v[208:211], 0
	v_cvt_pk_bf16_f32 v37, v38, v39
	v_cvt_pk_bf16_f32 v38, v32, v33
	v_cvt_pk_bf16_f32 v39, v34, v35
	ds_bpermute_b32 v32, v100, v36
	ds_bpermute_b32 v33, v100, v37
	ds_bpermute_b32 v34, v100, v38
	v_mfma_f32_16x16x32_bf16 v[64:67], v[174:177], v[208:211], 0
	ds_bpermute_b32 v35, v100, v39
	s_waitcnt lgkmcnt(4)
	global_store_dwordx4 v153, v[48:51], s[90:91] nt
	v_add_u32_e32 v153, s0, v153
	v_fmamk_f32 v230, v245, 0x3a800000, v207
	v_rsq_f32_e32 v230, v230
	v_mfma_f32_16x16x32_bf16 v[118:121], v[170:173], v[186:189], v[118:121]
	s_nop 0
	v_mul_f32_e32 v230, s36, v230
	v_mul_f32_e32 v20, v230, v20
	v_mul_f32_e32 v21, v230, v21
	v_mul_f32_e32 v22, v230, v22
	v_mfma_f32_16x16x32_bf16 v[114:117], v[178:181], v[186:189], v[114:117]
	v_mul_f32_e32 v23, v230, v23
	v_mul_f32_e32 v16, v230, v16
	v_mul_f32_e32 v17, v230, v17
	v_mul_f32_e32 v18, v230, v18
	v_mul_f32_e32 v19, v230, v19
	v_cvt_pk_bf16_f32 v20, v20, v21
	v_mfma_f32_16x16x32_bf16 v[102:105], v[170:173], v[194:197], v[102:105]
	v_cvt_pk_bf16_f32 v21, v22, v23
	v_cvt_pk_bf16_f32 v22, v16, v17
	v_cvt_pk_bf16_f32 v23, v18, v19
	ds_bpermute_b32 v16, v100, v20
	ds_bpermute_b32 v17, v100, v21
	ds_bpermute_b32 v18, v100, v22
	v_mfma_f32_16x16x32_bf16 v[96:99], v[178:181], v[194:197], v[96:99]
	ds_bpermute_b32 v19, v100, v23
	s_waitcnt lgkmcnt(4)
	global_store_dwordx4 v153, v[32:35], s[90:91] nt
	v_add_u32_e32 v153, s0, v153
	v_fmamk_f32 v230, v246, 0x3a800000, v207
	v_rsq_f32_e32 v230, v230
	v_mfma_f32_16x16x32_bf16 v[84:87], v[170:173], v[202:205], v[84:87]
	s_nop 0
	v_mul_f32_e32 v230, s36, v230
	v_mul_f32_e32 v4, v230, v4
	v_mul_f32_e32 v5, v230, v5
	v_mul_f32_e32 v6, v230, v6
	v_mfma_f32_16x16x32_bf16 v[80:83], v[178:181], v[202:205], v[80:83]
	v_mul_f32_e32 v7, v230, v7
	v_mul_f32_e32 v0, v230, v0
	v_mul_f32_e32 v1, v230, v1
	v_mul_f32_e32 v2, v230, v2
	v_mul_f32_e32 v3, v230, v3
	v_cvt_pk_bf16_f32 v4, v4, v5
	v_mfma_f32_16x16x32_bf16 v[68:71], v[170:173], v[226:229], v[68:71]
	v_cvt_pk_bf16_f32 v5, v6, v7
	v_cvt_pk_bf16_f32 v6, v0, v1
	v_cvt_pk_bf16_f32 v7, v2, v3
	ds_bpermute_b32 v0, v100, v4
	ds_bpermute_b32 v1, v100, v5
	ds_bpermute_b32 v2, v100, v6
	v_mfma_f32_16x16x32_bf16 v[64:67], v[178:181], v[226:229], v[64:67]
	ds_bpermute_b32 v3, v100, v7
	s_waitcnt lgkmcnt(4)
	global_store_dwordx4 v153, v[16:19], s[90:91] nt
	v_add_u32_e32 v153, s0, v153
	s_waitcnt lgkmcnt(0)
	global_store_dwordx4 v153, v[0:3], s[90:91] nt
	s_setprio 0
	s_barrier
	s_add_i32 s33, s33, s34
	v_lshl_add_u64 v[152:153], s[14:15], 0, v[132:133]
	s_mov_b32 m0, s33
	ds_read_b128 v[182:185], v156 offset:16384
	ds_read_b128 v[186:189], v156 offset:17408
	ds_read_b128 v[190:193], v156 offset:18432
	ds_read_b128 v[194:197], v156 offset:19456
	ds_read_b128 v[198:201], v156 offset:20480
	ds_read_b128 v[202:205], v156 offset:21504
	ds_read_b128 v[208:211], v156 offset:22528
	ds_read_b128 v[226:229], v156 offset:23552
	global_load_lds_dwordx4 v[152:153], off
	s_add_i32 m0, s33, 0x2000
	s_add_u32 s80, s14, 0x40000
	v_lshl_add_u64 v[212:213], s[14:15], 0, v[136:137]
	s_addc_u32 s81, s15, 0
	s_add_i32 s1, s1, s34
	global_load_lds_dwordx4 v[212:213], off
	v_lshl_add_u64 v[230:231], s[80:81], 0, v[132:133]
	s_mov_b32 m0, s1
	v_lshl_add_u64 v[232:233], s[28:29], 0, v[134:135]
	global_load_lds_dwordx4 v[230:231], off
	v_lshl_add_u64 v[230:231], s[80:81], 0, v[136:137]
	s_add_i32 m0, s1, 0x2000
	s_nop 0
	global_load_lds_dwordx4 v[230:231], off
	v_lshl_add_u64 v[230:231], s[28:29], 0, v[130:131]
	s_mov_b32 m0, s41
	s_nop 0
	global_load_lds_dwordx4 v[230:231], off
	s_mov_b32 m0, s60
	s_nop 0
	global_load_lds_dwordx4 v[232:233], off
	s_lshl_b32 s100, s10, 8
	s_cmp_lt_i32 s100, s49
	s_cselect_b32 s36, s25, 1.0
	s_mov_b32 s101, 0
	s_mov_b64 vcc, s[22:23]
	s_mov_b32 s46, s100
	s_and_b64 s[2:3], s[50:51], exec
	s_cbranch_scc0 .Lmy_st_nosplit_cd
	s_mul_hi_u32 s101, s100, s52
	s_mul_i32 s75, s101, s35
	s_sub_i32 s46, s100, s75
	s_add_i32 s75, s101, 1
	s_sub_i32 s2, s46, s35
	s_cmp_ge_u32 s46, s35
	s_cselect_b32 s101, s75, s101
	s_cselect_b32 s46, s2, s46
	s_add_i32 s75, s101, 1
	s_cmp_ge_u32 s46, s35
	s_cselect_b32 s101, s75, s101
	s_mul_hi_i32 s3, s4, s101
	s_mul_i32 s2, s4, s101
	s_lshl_b64 s[2:3], s[2:3], 1
	s_add_u32 vcc_lo, s22, s2
	s_addc_u32 vcc_hi, s23, s3
	s_mul_i32 s75, s101, s35
	s_sub_i32 s46, s100, s75

.Lmy_st_done_cd:
	s_add_u32 s90, s2, s100
	s_addc_u32 s91, s3, 0
	s_waitcnt vmcnt(24)
	s_waitcnt lgkmcnt(0)
	s_barrier
	s_setprio 1
	s_waitcnt lgkmcnt(0)
	v_mfma_f32_16x16x32_bf16 v[60:63], v[144:147], v[182:185], 0
	v_mfma_f32_16x16x32_bf16 v[56:59], v[158:161], v[182:185], 0
	v_mfma_f32_16x16x32_bf16 v[44:47], v[144:147], v[190:193], 0
	v_mfma_f32_16x16x32_bf16 v[40:43], v[158:161], v[190:193], 0
	v_mfma_f32_16x16x32_bf16 v[28:31], v[144:147], v[198:201], 0
	v_mfma_f32_16x16x32_bf16 v[24:27], v[158:161], v[198:201], 0
	v_mfma_f32_16x16x32_bf16 v[12:15], v[144:147], v[208:211], 0
	v_mfma_f32_16x16x32_bf16 v[8:11], v[158:161], v[208:211], 0
	v_mfma_f32_16x16x32_bf16 v[60:63], v[148:151], v[186:189], v[60:63]
	v_mfma_f32_16x16x32_bf16 v[56:59], v[162:165], v[186:189], v[56:59]
	v_mfma_f32_16x16x32_bf16 v[44:47], v[148:151], v[194:197], v[44:47]
	v_mfma_f32_16x16x32_bf16 v[40:43], v[162:165], v[194:197], v[40:43]
	v_mfma_f32_16x16x32_bf16 v[28:31], v[148:151], v[202:205], v[28:31]
	v_mfma_f32_16x16x32_bf16 v[24:27], v[162:165], v[202:205], v[24:27]
	v_mfma_f32_16x16x32_bf16 v[12:15], v[148:151], v[226:229], v[12:15]
	v_mfma_f32_16x16x32_bf16 v[8:11], v[162:165], v[226:229], v[8:11]
	s_setprio 0
	s_setprio 1
	v_mfma_f32_16x16x32_bf16 v[52:55], v[166:169], v[182:185], 0
	v_mfma_f32_16x16x32_bf16 v[48:51], v[174:177], v[182:185], 0
	v_mfma_f32_16x16x32_bf16 v[36:39], v[166:169], v[190:193], 0
	v_mfma_f32_16x16x32_bf16 v[32:35], v[174:177], v[190:193], 0
	v_mfma_f32_16x16x32_bf16 v[20:23], v[166:169], v[198:201], 0
	v_mfma_f32_16x16x32_bf16 v[16:19], v[174:177], v[198:201], 0
	v_mfma_f32_16x16x32_bf16 v[4:7], v[166:169], v[208:211], 0
	v_mfma_f32_16x16x32_bf16 v[0:3], v[174:177], v[208:211], 0
	v_mfma_f32_16x16x32_bf16 v[52:55], v[170:173], v[186:189], v[52:55]
	v_mfma_f32_16x16x32_bf16 v[48:51], v[178:181], v[186:189], v[48:51]
	v_mfma_f32_16x16x32_bf16 v[36:39], v[170:173], v[194:197], v[36:39]
	v_mfma_f32_16x16x32_bf16 v[32:35], v[178:181], v[194:197], v[32:35]
	v_mfma_f32_16x16x32_bf16 v[20:23], v[170:173], v[202:205], v[20:23]
	v_mfma_f32_16x16x32_bf16 v[16:19], v[178:181], v[202:205], v[16:19]
	v_mfma_f32_16x16x32_bf16 v[4:7], v[170:173], v[226:229], v[4:7]
	v_mfma_f32_16x16x32_bf16 v[0:3], v[178:181], v[226:229], v[0:3]
	s_setprio 0
	s_barrier
	s_add_i32 s1, 0, 0x18000
	v_add_u32_e32 v100, s1, v154
	s_add_i32 s33, 0, 0x1c000
	ds_read_b128 v[144:147], v100
	ds_read_b128 v[148:151], v100 offset:1024
	ds_read_b128 v[158:161], v100 offset:2048
	ds_read_b128 v[162:165], v100 offset:3072
	v_add_u32_e32 v100, s33, v154
	ds_read_b128 v[166:169], v100
	ds_read_b128 v[170:173], v100 offset:1024
	ds_read_b128 v[174:177], v100 offset:2048
	ds_read_b128 v[178:181], v100 offset:3072
	s_add_u32 s28, s28, 0x40000
	s_addc_u32 s29, s29, 0
	s_mov_b32 m0, s61
	v_lshl_add_u64 v[234:235], s[28:29], 0, v[130:131]
	ds_read_b128 v[182:185], v156 offset:32768
	ds_read_b128 v[186:189], v156 offset:33792
	ds_read_b128 v[190:193], v156 offset:34816
	ds_read_b128 v[194:197], v156 offset:35840
	ds_read_b128 v[198:201], v156 offset:36864
	ds_read_b128 v[202:205], v156 offset:37888
	ds_read_b128 v[208:211], v156 offset:38912
	ds_read_b128 v[226:229], v156 offset:39936
	global_load_lds_dwordx4 v[234:235], off
	v_lshl_add_u64 v[234:235], s[28:29], 0, v[134:135]
	s_mov_b32 m0, s69
	s_nop 0
	global_load_lds_dwordx4 v[234:235], off
	s_lshl_b32 s46, s40, 8
	s_add_i32 s46, s46, s84
	v_or_b32_e32 v100, s46, v139
	v_lshlrev_b32_e32 v100, 2, v100
	global_load_dword v236, v100, s[66:67]
	global_load_dword v237, v100, s[66:67] offset:64
	global_load_dword v238, v100, s[66:67] offset:128
	global_load_dword v239, v100, s[66:67] offset:192
	global_load_dword v240, v100, s[66:67] offset:512
	global_load_dword v244, v100, s[66:67] offset:576
	global_load_dword v245, v100, s[66:67] offset:640
	global_load_dword v246, v100, s[66:67] offset:704
	s_waitcnt vmcnt(24)
	s_waitcnt lgkmcnt(0)
	s_barrier
	s_setprio 1
	s_waitcnt lgkmcnt(0)
	v_mfma_f32_16x16x32_bf16 v[126:129], v[144:147], v[182:185], v[126:129]
	v_mfma_f32_16x16x32_bf16 v[122:125], v[158:161], v[182:185], v[122:125]
	v_mfma_f32_16x16x32_bf16 v[110:113], v[144:147], v[190:193], v[110:113]
	v_mfma_f32_16x16x32_bf16 v[106:109], v[158:161], v[190:193], v[106:109]
	v_mfma_f32_16x16x32_bf16 v[92:95], v[144:147], v[198:201], v[92:95]
	v_mfma_f32_16x16x32_bf16 v[88:91], v[158:161], v[198:201], v[88:91]
	v_mfma_f32_16x16x32_bf16 v[76:79], v[144:147], v[208:211], v[76:79]
	v_mfma_f32_16x16x32_bf16 v[72:75], v[158:161], v[208:211], v[72:75]
	v_mfma_f32_16x16x32_bf16 v[126:129], v[148:151], v[186:189], v[126:129]
	v_mfma_f32_16x16x32_bf16 v[122:125], v[162:165], v[186:189], v[122:125]
	v_mfma_f32_16x16x32_bf16 v[110:113], v[148:151], v[194:197], v[110:113]
	v_mfma_f32_16x16x32_bf16 v[106:109], v[162:165], v[194:197], v[106:109]
	v_mfma_f32_16x16x32_bf16 v[92:95], v[148:151], v[202:205], v[92:95]
	v_mfma_f32_16x16x32_bf16 v[88:91], v[162:165], v[202:205], v[88:91]
	v_mfma_f32_16x16x32_bf16 v[76:79], v[148:151], v[226:229], v[76:79]
	v_mfma_f32_16x16x32_bf16 v[72:75], v[162:165], v[226:229], v[72:75]
	s_setprio 0
	s_setprio 1
	v_mfma_f32_16x16x32_bf16 v[118:121], v[166:169], v[182:185], v[118:121]
	v_mfma_f32_16x16x32_bf16 v[114:117], v[174:177], v[182:185], v[114:117]
	v_mfma_f32_16x16x32_bf16 v[102:105], v[166:169], v[190:193], v[102:105]
	v_mfma_f32_16x16x32_bf16 v[96:99], v[174:177], v[190:193], v[96:99]
	v_mfma_f32_16x16x32_bf16 v[84:87], v[166:169], v[198:201], v[84:87]
	v_mfma_f32_16x16x32_bf16 v[80:83], v[174:177], v[198:201], v[80:83]
	v_mfma_f32_16x16x32_bf16 v[68:71], v[166:169], v[208:211], v[68:71]
	v_mfma_f32_16x16x32_bf16 v[64:67], v[174:177], v[208:211], v[64:67]
	v_mfma_f32_16x16x32_bf16 v[118:121], v[170:173], v[186:189], v[118:121]
	v_mfma_f32_16x16x32_bf16 v[114:117], v[178:181], v[186:189], v[114:117]
	v_mfma_f32_16x16x32_bf16 v[102:105], v[170:173], v[194:197], v[102:105]
	v_mfma_f32_16x16x32_bf16 v[96:99], v[178:181], v[194:197], v[96:99]
	v_mfma_f32_16x16x32_bf16 v[84:87], v[170:173], v[202:205], v[84:87]
	v_mfma_f32_16x16x32_bf16 v[80:83], v[178:181], v[202:205], v[80:83]
	v_mfma_f32_16x16x32_bf16 v[68:71], v[170:173], v[226:229], v[68:71]
	v_mfma_f32_16x16x32_bf16 v[64:67], v[178:181], v[226:229], v[64:67]
	s_setprio 0
	s_barrier
	s_add_i32 s1, s1, s34
	v_lshl_add_u64 v[152:153], v[152:153], 0, s[86:87]
	s_mov_b32 m0, s1
	ds_read_b128 v[182:185], v156 offset:49152
	ds_read_b128 v[186:189], v156 offset:50176
	ds_read_b128 v[190:193], v156 offset:51200
	ds_read_b128 v[194:197], v156 offset:52224
	ds_read_b128 v[198:201], v156 offset:53248
	ds_read_b128 v[202:205], v156 offset:54272
	ds_read_b128 v[208:211], v156 offset:55296
	ds_read_b128 v[226:229], v156 offset:56320
	global_load_lds_dwordx4 v[152:153], off
	s_add_i32 m0, s1, 0x2000
	s_add_u32 s14, s14, 0x40080
	v_lshl_add_u64 v[152:153], v[212:213], 0, s[86:87]
	s_addc_u32 s15, s15, 0
	s_add_i32 s1, s33, s34
	global_load_lds_dwordx4 v[152:153], off
	v_lshl_add_u64 v[152:153], s[14:15], 0, v[132:133]
	s_mov_b32 m0, s1
	s_nop 0
	global_load_lds_dwordx4 v[152:153], off
	v_lshl_add_u64 v[152:153], s[14:15], 0, v[136:137]
	s_add_i32 m0, s1, 0x2000
	s_nop 0
	global_load_lds_dwordx4 v[152:153], off
	v_lshl_add_u64 v[152:153], v[230:231], 0, s[86:87]
	s_mov_b32 m0, s89
	s_nop 0
	global_load_lds_dwordx4 v[152:153], off
	v_lshl_add_u64 v[152:153], v[232:233], 0, s[86:87]
	s_mov_b32 m0, s92
	s_nop 0
	global_load_lds_dwordx4 v[152:153], off
	s_waitcnt vmcnt(16)
	s_waitcnt lgkmcnt(0)
	s_barrier
	s_setprio 1
	s_waitcnt lgkmcnt(0)
	v_mfma_f32_16x16x32_bf16 v[60:63], v[144:147], v[182:185], v[60:63]
	v_mfma_f32_16x16x32_bf16 v[56:59], v[158:161], v[182:185], v[56:59]
	v_mfma_f32_16x16x32_bf16 v[44:47], v[144:147], v[190:193], v[44:47]
	v_mfma_f32_16x16x32_bf16 v[40:43], v[158:161], v[190:193], v[40:43]
	v_mfma_f32_16x16x32_bf16 v[28:31], v[144:147], v[198:201], v[28:31]
	v_mfma_f32_16x16x32_bf16 v[24:27], v[158:161], v[198:201], v[24:27]
	v_mfma_f32_16x16x32_bf16 v[12:15], v[144:147], v[208:211], v[12:15]
	v_mfma_f32_16x16x32_bf16 v[8:11], v[158:161], v[208:211], v[8:11]
	v_mfma_f32_16x16x32_bf16 v[60:63], v[148:151], v[186:189], v[60:63]
	v_mfma_f32_16x16x32_bf16 v[56:59], v[162:165], v[186:189], v[56:59]
	v_mfma_f32_16x16x32_bf16 v[44:47], v[148:151], v[194:197], v[44:47]
	v_mfma_f32_16x16x32_bf16 v[40:43], v[162:165], v[194:197], v[40:43]
	v_mfma_f32_16x16x32_bf16 v[28:31], v[148:151], v[202:205], v[28:31]
	v_mfma_f32_16x16x32_bf16 v[24:27], v[162:165], v[202:205], v[24:27]
	v_mfma_f32_16x16x32_bf16 v[12:15], v[148:151], v[226:229], v[12:15]
	v_mfma_f32_16x16x32_bf16 v[8:11], v[162:165], v[226:229], v[8:11]
	s_setprio 0
	s_setprio 1
	v_mfma_f32_16x16x32_bf16 v[52:55], v[166:169], v[182:185], v[52:55]
	v_mfma_f32_16x16x32_bf16 v[48:51], v[174:177], v[182:185], v[48:51]
	v_mfma_f32_16x16x32_bf16 v[36:39], v[166:169], v[190:193], v[36:39]
	v_mfma_f32_16x16x32_bf16 v[32:35], v[174:177], v[190:193], v[32:35]
	v_mfma_f32_16x16x32_bf16 v[20:23], v[166:169], v[198:201], v[20:23]
	v_mfma_f32_16x16x32_bf16 v[16:19], v[174:177], v[198:201], v[16:19]
	v_mfma_f32_16x16x32_bf16 v[4:7], v[166:169], v[208:211], v[4:7]
	v_mfma_f32_16x16x32_bf16 v[0:3], v[174:177], v[208:211], v[0:3]
	v_mfma_f32_16x16x32_bf16 v[52:55], v[170:173], v[186:189], v[52:55]
	v_mfma_f32_16x16x32_bf16 v[48:51], v[178:181], v[186:189], v[48:51]
	v_mfma_f32_16x16x32_bf16 v[36:39], v[170:173], v[194:197], v[36:39]
	v_mfma_f32_16x16x32_bf16 v[32:35], v[178:181], v[194:197], v[32:35]
	v_mfma_f32_16x16x32_bf16 v[20:23], v[170:173], v[202:205], v[20:23]
	v_mfma_f32_16x16x32_bf16 v[16:19], v[178:181], v[202:205], v[16:19]
	v_mfma_f32_16x16x32_bf16 v[4:7], v[170:173], v[226:229], v[4:7]
	v_mfma_f32_16x16x32_bf16 v[0:3], v[178:181], v[226:229], v[0:3]
	s_setprio 0
	s_barrier
	s_add_i32 s73, s73, 2
	s_add_u32 s12, s12, 0x100
	s_addc_u32 s13, s13, 0
	s_add_u32 s54, s54, 0x100
	s_addc_u32 s55, s55, 0
	s_nop 0
.LBB0_396:
	s_add_u32 s1, s12, 0xfffc0080
	s_addc_u32 s14, s13, -1
	s_add_i32 s33, 0, 0x10000
	s_cmp_eq_u32 s73, 12
	s_cselect_b32 s29, s11, s14
	s_cselect_b32 s28, s30, s1
	v_add_u32_e32 v100, s33, v154
	s_cselect_b32 s15, s31, s55
	s_cselect_b32 s14, s47, s54
	s_add_i32 s1, 0, 0x14000
	ds_read_b128 v[144:147], v100
	ds_read_b128 v[148:151], v100 offset:1024
	ds_read_b128 v[158:161], v100 offset:2048
	ds_read_b128 v[162:165], v100 offset:3072
	v_add_u32_e32 v100, s1, v154
	ds_read_b128 v[166:169], v100
	ds_read_b128 v[170:173], v100 offset:1024
	ds_read_b128 v[174:177], v100 offset:2048
	ds_read_b128 v[178:181], v100 offset:3072
	v_lshl_add_u64 v[152:153], s[12:13], 0, v[140:141]
	s_add_i32 m0, s41, 0xc000
	ds_read_b128 v[182:185], v156
	ds_read_b128 v[186:189], v156 offset:1024
	ds_read_b128 v[190:193], v156 offset:2048
	ds_read_b128 v[194:197], v156 offset:3072
	ds_read_b128 v[198:201], v156 offset:4096
	ds_read_b128 v[202:205], v156 offset:5120
	ds_read_b128 v[208:211], v156 offset:6144
	ds_read_b128 v[226:229], v156 offset:7168
	global_load_lds_dwordx4 v[152:153], off
	v_lshl_add_u64 v[152:153], s[12:13], 0, v[142:143]
	s_add_i32 m0, s41, 0xe000
	s_nop 0
	global_load_lds_dwordx4 v[152:153], off
	s_waitcnt vmcnt(8)
	s_waitcnt lgkmcnt(0)
	s_barrier
	s_setprio 1
	s_waitcnt lgkmcnt(0)
	v_mfma_f32_16x16x32_bf16 v[126:129], v[144:147], v[182:185], v[126:129]
	v_mfma_f32_16x16x32_bf16 v[122:125], v[158:161], v[182:185], v[122:125]
	v_mfma_f32_16x16x32_bf16 v[110:113], v[144:147], v[190:193], v[110:113]
	v_mfma_f32_16x16x32_bf16 v[106:109], v[158:161], v[190:193], v[106:109]
	v_mfma_f32_16x16x32_bf16 v[92:95], v[144:147], v[198:201], v[92:95]
	v_mfma_f32_16x16x32_bf16 v[88:91], v[158:161], v[198:201], v[88:91]
	v_mfma_f32_16x16x32_bf16 v[76:79], v[144:147], v[208:211], v[76:79]
	v_mfma_f32_16x16x32_bf16 v[72:75], v[158:161], v[208:211], v[72:75]
	v_mfma_f32_16x16x32_bf16 v[126:129], v[148:151], v[186:189], v[126:129]
	v_mfma_f32_16x16x32_bf16 v[122:125], v[162:165], v[186:189], v[122:125]
	v_mfma_f32_16x16x32_bf16 v[110:113], v[148:151], v[194:197], v[110:113]
	v_mfma_f32_16x16x32_bf16 v[106:109], v[162:165], v[194:197], v[106:109]
	v_mfma_f32_16x16x32_bf16 v[92:95], v[148:151], v[202:205], v[92:95]
	v_mfma_f32_16x16x32_bf16 v[88:91], v[162:165], v[202:205], v[88:91]
	v_mfma_f32_16x16x32_bf16 v[76:79], v[148:151], v[226:229], v[76:79]
	v_mfma_f32_16x16x32_bf16 v[72:75], v[162:165], v[226:229], v[72:75]
	s_setprio 0
	s_setprio 1
	v_mfma_f32_16x16x32_bf16 v[118:121], v[166:169], v[182:185], v[118:121]
	v_mfma_f32_16x16x32_bf16 v[114:117], v[174:177], v[182:185], v[114:117]
	v_mfma_f32_16x16x32_bf16 v[102:105], v[166:169], v[190:193], v[102:105]
	v_mfma_f32_16x16x32_bf16 v[96:99], v[174:177], v[190:193], v[96:99]
	v_mfma_f32_16x16x32_bf16 v[84:87], v[166:169], v[198:201], v[84:87]
	v_mfma_f32_16x16x32_bf16 v[80:83], v[174:177], v[198:201], v[80:83]
	v_mfma_f32_16x16x32_bf16 v[68:71], v[166:169], v[208:211], v[68:71]
	v_mfma_f32_16x16x32_bf16 v[64:67], v[174:177], v[208:211], v[64:67]
	v_mfma_f32_16x16x32_bf16 v[118:121], v[170:173], v[186:189], v[118:121]
	v_mfma_f32_16x16x32_bf16 v[114:117], v[178:181], v[186:189], v[114:117]
	v_mfma_f32_16x16x32_bf16 v[102:105], v[170:173], v[194:197], v[102:105]
	v_mfma_f32_16x16x32_bf16 v[96:99], v[178:181], v[194:197], v[96:99]
	v_mfma_f32_16x16x32_bf16 v[84:87], v[170:173], v[202:205], v[84:87]
	v_mfma_f32_16x16x32_bf16 v[80:83], v[178:181], v[202:205], v[80:83]
	v_mfma_f32_16x16x32_bf16 v[68:71], v[170:173], v[226:229], v[68:71]
	v_mfma_f32_16x16x32_bf16 v[64:67], v[178:181], v[226:229], v[64:67]
	s_setprio 0
	s_barrier
	s_add_i32 s33, s33, s34
	v_lshl_add_u64 v[152:153], s[14:15], 0, v[132:133]
	s_mov_b32 m0, s33
	ds_read_b128 v[182:185], v156 offset:16384
	ds_read_b128 v[186:189], v156 offset:17408
	ds_read_b128 v[190:193], v156 offset:18432
	ds_read_b128 v[194:197], v156 offset:19456
	ds_read_b128 v[198:201], v156 offset:20480
	ds_read_b128 v[202:205], v156 offset:21504
	ds_read_b128 v[208:211], v156 offset:22528
	ds_read_b128 v[226:229], v156 offset:23552
	global_load_lds_dwordx4 v[152:153], off
	s_add_i32 m0, s33, 0x2000
	s_add_u32 s80, s14, 0x40000
	v_lshl_add_u64 v[212:213], s[14:15], 0, v[136:137]
	s_addc_u32 s81, s15, 0
	s_add_i32 s1, s1, s34
	global_load_lds_dwordx4 v[212:213], off
	v_lshl_add_u64 v[230:231], s[80:81], 0, v[132:133]
	s_mov_b32 m0, s1
	v_lshl_add_u64 v[232:233], s[28:29], 0, v[134:135]
	global_load_lds_dwordx4 v[230:231], off
	v_lshl_add_u64 v[230:231], s[80:81], 0, v[136:137]
	s_add_i32 m0, s1, 0x2000
	s_nop 0
	global_load_lds_dwordx4 v[230:231], off
	v_lshl_add_u64 v[230:231], s[28:29], 0, v[130:131]
	s_mov_b32 m0, s41
	s_nop 0
	global_load_lds_dwordx4 v[230:231], off
	s_mov_b32 m0, s60
	s_nop 0
	global_load_lds_dwordx4 v[232:233], off
	s_waitcnt vmcnt(8)
	s_waitcnt lgkmcnt(0)
	s_barrier
	s_setprio 1
	s_waitcnt lgkmcnt(0)
	v_mfma_f32_16x16x32_bf16 v[60:63], v[144:147], v[182:185], v[60:63]
	v_mfma_f32_16x16x32_bf16 v[56:59], v[158:161], v[182:185], v[56:59]
	v_mfma_f32_16x16x32_bf16 v[44:47], v[144:147], v[190:193], v[44:47]
	v_mfma_f32_16x16x32_bf16 v[40:43], v[158:161], v[190:193], v[40:43]
	v_mfma_f32_16x16x32_bf16 v[28:31], v[144:147], v[198:201], v[28:31]
	v_mfma_f32_16x16x32_bf16 v[24:27], v[158:161], v[198:201], v[24:27]
	v_mfma_f32_16x16x32_bf16 v[12:15], v[144:147], v[208:211], v[12:15]
	v_mfma_f32_16x16x32_bf16 v[8:11], v[158:161], v[208:211], v[8:11]
	v_mfma_f32_16x16x32_bf16 v[60:63], v[148:151], v[186:189], v[60:63]
	v_mfma_f32_16x16x32_bf16 v[56:59], v[162:165], v[186:189], v[56:59]
	v_mfma_f32_16x16x32_bf16 v[44:47], v[148:151], v[194:197], v[44:47]
	v_mfma_f32_16x16x32_bf16 v[40:43], v[162:165], v[194:197], v[40:43]
	v_mfma_f32_16x16x32_bf16 v[28:31], v[148:151], v[202:205], v[28:31]
	v_mfma_f32_16x16x32_bf16 v[24:27], v[162:165], v[202:205], v[24:27]
	v_mfma_f32_16x16x32_bf16 v[12:15], v[148:151], v[226:229], v[12:15]
	v_mfma_f32_16x16x32_bf16 v[8:11], v[162:165], v[226:229], v[8:11]
	s_setprio 0
	s_setprio 1
	v_mfma_f32_16x16x32_bf16 v[52:55], v[166:169], v[182:185], v[52:55]
	v_mfma_f32_16x16x32_bf16 v[48:51], v[174:177], v[182:185], v[48:51]
	v_mfma_f32_16x16x32_bf16 v[36:39], v[166:169], v[190:193], v[36:39]
	v_mfma_f32_16x16x32_bf16 v[32:35], v[174:177], v[190:193], v[32:35]
	v_mfma_f32_16x16x32_bf16 v[20:23], v[166:169], v[198:201], v[20:23]
	v_mfma_f32_16x16x32_bf16 v[16:19], v[174:177], v[198:201], v[16:19]
	v_mfma_f32_16x16x32_bf16 v[4:7], v[166:169], v[208:211], v[4:7]
	v_mfma_f32_16x16x32_bf16 v[0:3], v[174:177], v[208:211], v[0:3]
	v_mfma_f32_16x16x32_bf16 v[52:55], v[170:173], v[186:189], v[52:55]
	v_mfma_f32_16x16x32_bf16 v[48:51], v[178:181], v[186:189], v[48:51]
	v_mfma_f32_16x16x32_bf16 v[36:39], v[170:173], v[194:197], v[36:39]
	v_mfma_f32_16x16x32_bf16 v[32:35], v[178:181], v[194:197], v[32:35]
	v_mfma_f32_16x16x32_bf16 v[20:23], v[170:173], v[202:205], v[20:23]
	v_mfma_f32_16x16x32_bf16 v[16:19], v[178:181], v[202:205], v[16:19]
	v_mfma_f32_16x16x32_bf16 v[4:7], v[170:173], v[226:229], v[4:7]
	v_mfma_f32_16x16x32_bf16 v[0:3], v[178:181], v[226:229], v[0:3]
	s_setprio 0
	s_barrier
	s_add_i32 s1, 0, 0x18000
	v_add_u32_e32 v100, s1, v154
	s_add_i32 s33, 0, 0x1c000
	ds_read_b128 v[144:147], v100
	ds_read_b128 v[148:151], v100 offset:1024
	ds_read_b128 v[158:161], v100 offset:2048
	ds_read_b128 v[162:165], v100 offset:3072
	v_add_u32_e32 v100, s33, v154
	ds_read_b128 v[166:169], v100
	ds_read_b128 v[170:173], v100 offset:1024
	ds_read_b128 v[174:177], v100 offset:2048
	ds_read_b128 v[178:181], v100 offset:3072
	s_add_u32 s28, s28, 0x40000
	s_addc_u32 s29, s29, 0
	s_mov_b32 m0, s61
	v_lshl_add_u64 v[234:235], s[28:29], 0, v[130:131]
	ds_read_b128 v[182:185], v156 offset:32768
	ds_read_b128 v[186:189], v156 offset:33792
	ds_read_b128 v[190:193], v156 offset:34816
	ds_read_b128 v[194:197], v156 offset:35840
	ds_read_b128 v[198:201], v156 offset:36864
	ds_read_b128 v[202:205], v156 offset:37888
	ds_read_b128 v[208:211], v156 offset:38912
	ds_read_b128 v[226:229], v156 offset:39936
	global_load_lds_dwordx4 v[234:235], off
	v_lshl_add_u64 v[234:235], s[28:29], 0, v[134:135]
	s_mov_b32 m0, s69
	s_nop 0
	global_load_lds_dwordx4 v[234:235], off
	s_waitcnt vmcnt(8)
	s_waitcnt lgkmcnt(0)
	s_barrier
	s_setprio 1
	s_waitcnt lgkmcnt(0)
	v_mfma_f32_16x16x32_bf16 v[126:129], v[144:147], v[182:185], v[126:129]
	v_mfma_f32_16x16x32_bf16 v[122:125], v[158:161], v[182:185], v[122:125]
	v_mfma_f32_16x16x32_bf16 v[110:113], v[144:147], v[190:193], v[110:113]
	v_mfma_f32_16x16x32_bf16 v[106:109], v[158:161], v[190:193], v[106:109]
	v_mfma_f32_16x16x32_bf16 v[92:95], v[144:147], v[198:201], v[92:95]
	v_mfma_f32_16x16x32_bf16 v[88:91], v[158:161], v[198:201], v[88:91]
	v_mfma_f32_16x16x32_bf16 v[76:79], v[144:147], v[208:211], v[76:79]
	v_mfma_f32_16x16x32_bf16 v[72:75], v[158:161], v[208:211], v[72:75]
	v_mfma_f32_16x16x32_bf16 v[126:129], v[148:151], v[186:189], v[126:129]
	v_mfma_f32_16x16x32_bf16 v[122:125], v[162:165], v[186:189], v[122:125]
	v_mfma_f32_16x16x32_bf16 v[110:113], v[148:151], v[194:197], v[110:113]
	v_mfma_f32_16x16x32_bf16 v[106:109], v[162:165], v[194:197], v[106:109]
	v_mfma_f32_16x16x32_bf16 v[92:95], v[148:151], v[202:205], v[92:95]
	v_mfma_f32_16x16x32_bf16 v[88:91], v[162:165], v[202:205], v[88:91]
	v_mfma_f32_16x16x32_bf16 v[76:79], v[148:151], v[226:229], v[76:79]
	v_mfma_f32_16x16x32_bf16 v[72:75], v[162:165], v[226:229], v[72:75]
	s_setprio 0
	s_setprio 1
	v_mfma_f32_16x16x32_bf16 v[118:121], v[166:169], v[182:185], v[118:121]
	v_mfma_f32_16x16x32_bf16 v[114:117], v[174:177], v[182:185], v[114:117]
	v_mfma_f32_16x16x32_bf16 v[102:105], v[166:169], v[190:193], v[102:105]
	v_mfma_f32_16x16x32_bf16 v[96:99], v[174:177], v[190:193], v[96:99]
	v_mfma_f32_16x16x32_bf16 v[84:87], v[166:169], v[198:201], v[84:87]
	v_mfma_f32_16x16x32_bf16 v[80:83], v[174:177], v[198:201], v[80:83]
	v_mfma_f32_16x16x32_bf16 v[68:71], v[166:169], v[208:211], v[68:71]
	v_mfma_f32_16x16x32_bf16 v[64:67], v[174:177], v[208:211], v[64:67]
	v_mfma_f32_16x16x32_bf16 v[118:121], v[170:173], v[186:189], v[118:121]
	v_mfma_f32_16x16x32_bf16 v[114:117], v[178:181], v[186:189], v[114:117]
	v_mfma_f32_16x16x32_bf16 v[102:105], v[170:173], v[194:197], v[102:105]
	v_mfma_f32_16x16x32_bf16 v[96:99], v[178:181], v[194:197], v[96:99]
	v_mfma_f32_16x16x32_bf16 v[84:87], v[170:173], v[202:205], v[84:87]
	v_mfma_f32_16x16x32_bf16 v[80:83], v[178:181], v[202:205], v[80:83]
	v_mfma_f32_16x16x32_bf16 v[68:71], v[170:173], v[226:229], v[68:71]
	v_mfma_f32_16x16x32_bf16 v[64:67], v[178:181], v[226:229], v[64:67]
	s_setprio 0
	s_barrier
	s_add_i32 s1, s1, s34
	v_lshl_add_u64 v[152:153], v[152:153], 0, s[86:87]
	s_mov_b32 m0, s1
	ds_read_b128 v[182:185], v156 offset:49152
	ds_read_b128 v[186:189], v156 offset:50176
	ds_read_b128 v[190:193], v156 offset:51200
	ds_read_b128 v[194:197], v156 offset:52224
	ds_read_b128 v[198:201], v156 offset:53248
	ds_read_b128 v[202:205], v156 offset:54272
	ds_read_b128 v[208:211], v156 offset:55296
	ds_read_b128 v[226:229], v156 offset:56320
	global_load_lds_dwordx4 v[152:153], off
	s_add_i32 m0, s1, 0x2000
	s_add_u32 s14, s14, 0x40080
	v_lshl_add_u64 v[152:153], v[212:213], 0, s[86:87]
	s_addc_u32 s15, s15, 0
	s_add_i32 s1, s33, s34
	global_load_lds_dwordx4 v[152:153], off
	v_lshl_add_u64 v[152:153], s[14:15], 0, v[132:133]
	s_mov_b32 m0, s1
	s_nop 0
	global_load_lds_dwordx4 v[152:153], off
	v_lshl_add_u64 v[152:153], s[14:15], 0, v[136:137]
	s_add_i32 m0, s1, 0x2000
	s_nop 0
	global_load_lds_dwordx4 v[152:153], off
	v_lshl_add_u64 v[152:153], v[230:231], 0, s[86:87]
	s_mov_b32 m0, s89
	s_nop 0
	global_load_lds_dwordx4 v[152:153], off
	v_lshl_add_u64 v[152:153], v[232:233], 0, s[86:87]
	s_mov_b32 m0, s92
	s_nop 0
	global_load_lds_dwordx4 v[152:153], off
	s_waitcnt vmcnt(8)
	s_waitcnt lgkmcnt(0)
	s_barrier
	s_setprio 1
	s_waitcnt lgkmcnt(0)
	v_mfma_f32_16x16x32_bf16 v[60:63], v[144:147], v[182:185], v[60:63]
	v_mfma_f32_16x16x32_bf16 v[56:59], v[158:161], v[182:185], v[56:59]
	v_mfma_f32_16x16x32_bf16 v[44:47], v[144:147], v[190:193], v[44:47]
	v_mfma_f32_16x16x32_bf16 v[40:43], v[158:161], v[190:193], v[40:43]
	v_mfma_f32_16x16x32_bf16 v[28:31], v[144:147], v[198:201], v[28:31]
	v_mfma_f32_16x16x32_bf16 v[24:27], v[158:161], v[198:201], v[24:27]
	v_mfma_f32_16x16x32_bf16 v[12:15], v[144:147], v[208:211], v[12:15]
	v_mfma_f32_16x16x32_bf16 v[8:11], v[158:161], v[208:211], v[8:11]
	v_mfma_f32_16x16x32_bf16 v[60:63], v[148:151], v[186:189], v[60:63]
	v_mfma_f32_16x16x32_bf16 v[56:59], v[162:165], v[186:189], v[56:59]
	v_mfma_f32_16x16x32_bf16 v[44:47], v[148:151], v[194:197], v[44:47]
	v_mfma_f32_16x16x32_bf16 v[40:43], v[162:165], v[194:197], v[40:43]
	v_mfma_f32_16x16x32_bf16 v[28:31], v[148:151], v[202:205], v[28:31]
	v_mfma_f32_16x16x32_bf16 v[24:27], v[162:165], v[202:205], v[24:27]
	v_mfma_f32_16x16x32_bf16 v[12:15], v[148:151], v[226:229], v[12:15]
	v_mfma_f32_16x16x32_bf16 v[8:11], v[162:165], v[226:229], v[8:11]
	s_setprio 0
	s_setprio 1
	v_mfma_f32_16x16x32_bf16 v[52:55], v[166:169], v[182:185], v[52:55]
	v_mfma_f32_16x16x32_bf16 v[48:51], v[174:177], v[182:185], v[48:51]
	v_mfma_f32_16x16x32_bf16 v[36:39], v[166:169], v[190:193], v[36:39]
	v_mfma_f32_16x16x32_bf16 v[32:35], v[174:177], v[190:193], v[32:35]
	v_mfma_f32_16x16x32_bf16 v[20:23], v[166:169], v[198:201], v[20:23]
	v_mfma_f32_16x16x32_bf16 v[16:19], v[174:177], v[198:201], v[16:19]
	v_mfma_f32_16x16x32_bf16 v[4:7], v[166:169], v[208:211], v[4:7]
	v_mfma_f32_16x16x32_bf16 v[0:3], v[174:177], v[208:211], v[0:3]
	v_mfma_f32_16x16x32_bf16 v[52:55], v[170:173], v[186:189], v[52:55]
	v_mfma_f32_16x16x32_bf16 v[48:51], v[178:181], v[186:189], v[48:51]
	v_mfma_f32_16x16x32_bf16 v[36:39], v[170:173], v[194:197], v[36:39]
	v_mfma_f32_16x16x32_bf16 v[32:35], v[178:181], v[194:197], v[32:35]
	v_mfma_f32_16x16x32_bf16 v[20:23], v[170:173], v[202:205], v[20:23]
	v_mfma_f32_16x16x32_bf16 v[16:19], v[178:181], v[202:205], v[16:19]
	v_mfma_f32_16x16x32_bf16 v[4:7], v[170:173], v[226:229], v[4:7]
	v_mfma_f32_16x16x32_bf16 v[0:3], v[178:181], v[226:229], v[0:3]
	s_setprio 0
	s_barrier
	s_add_i32 s73, s73, 2
	s_add_u32 s12, s12, 0x100
	s_addc_u32 s13, s13, 0
	s_add_u32 s54, s54, 0x100
	s_addc_u32 s55, s55, 0
	s_cmp_gt_u32 s73, s97
	s_cbranch_scc0 .LBB0_396
.LBB0_399:
	s_cmp_lg_u32 s82, 0
	s_cbranch_scc0 .Lmy_b16_inpl
	s_add_u32 s1, s12, 0xfffc0080
	s_addc_u32 s14, s13, -1
	s_add_i32 s33, 0, 0x10000
	s_cmp_eq_u32 s73, 12
	s_cselect_b32 s29, s11, s14
	s_cselect_b32 s28, s30, s1
	v_add_u32_e32 v100, s33, v154
	s_cselect_b32 s15, s31, s55
	s_cselect_b32 s14, s47, s54
	s_add_i32 s1, 0, 0x14000
	ds_read_b128 v[144:147], v100
	ds_read_b128 v[148:151], v100 offset:1024
	ds_read_b128 v[158:161], v100 offset:2048
	ds_read_b128 v[162:165], v100 offset:3072
	v_add_u32_e32 v100, s1, v154
	ds_read_b128 v[166:169], v100
	ds_read_b128 v[170:173], v100 offset:1024
	ds_read_b128 v[174:177], v100 offset:2048
	ds_read_b128 v[178:181], v100 offset:3072
	v_lshl_add_u64 v[152:153], s[12:13], 0, v[140:141]
	s_add_i32 m0, s41, 0xc000
	ds_read_b128 v[182:185], v156
	ds_read_b128 v[186:189], v156 offset:1024
	ds_read_b128 v[190:193], v156 offset:2048
	ds_read_b128 v[194:197], v156 offset:3072
	ds_read_b128 v[198:201], v156 offset:4096
	ds_read_b128 v[202:205], v156 offset:5120
	ds_read_b128 v[208:211], v156 offset:6144
	ds_read_b128 v[226:229], v156 offset:7168
	global_load_lds_dwordx4 v[152:153], off
	v_lshl_add_u64 v[152:153], s[12:13], 0, v[142:143]
	s_add_i32 m0, s41, 0xe000
	s_nop 0
	global_load_lds_dwordx4 v[152:153], off
	s_waitcnt vmcnt(8)
	s_waitcnt lgkmcnt(0)
	s_barrier
	s_setprio 1
	s_waitcnt lgkmcnt(0)
	v_mfma_f32_16x16x32_bf16 v[126:129], v[144:147], v[182:185], v[126:129]
	v_mfma_f32_16x16x32_bf16 v[122:125], v[158:161], v[182:185], v[122:125]
	v_mfma_f32_16x16x32_bf16 v[110:113], v[144:147], v[190:193], v[110:113]
	v_mfma_f32_16x16x32_bf16 v[106:109], v[158:161], v[190:193], v[106:109]
	v_mfma_f32_16x16x32_bf16 v[92:95], v[144:147], v[198:201], v[92:95]
	v_mfma_f32_16x16x32_bf16 v[88:91], v[158:161], v[198:201], v[88:91]
	v_mfma_f32_16x16x32_bf16 v[76:79], v[144:147], v[208:211], v[76:79]
	v_mfma_f32_16x16x32_bf16 v[72:75], v[158:161], v[208:211], v[72:75]
	v_mfma_f32_16x16x32_bf16 v[126:129], v[148:151], v[186:189], v[126:129]
	v_mfma_f32_16x16x32_bf16 v[122:125], v[162:165], v[186:189], v[122:125]
	v_mfma_f32_16x16x32_bf16 v[110:113], v[148:151], v[194:197], v[110:113]
	v_mfma_f32_16x16x32_bf16 v[106:109], v[162:165], v[194:197], v[106:109]
	v_mfma_f32_16x16x32_bf16 v[92:95], v[148:151], v[202:205], v[92:95]
	v_mfma_f32_16x16x32_bf16 v[88:91], v[162:165], v[202:205], v[88:91]
	v_mfma_f32_16x16x32_bf16 v[76:79], v[148:151], v[226:229], v[76:79]
	v_mfma_f32_16x16x32_bf16 v[72:75], v[162:165], v[226:229], v[72:75]
	s_setprio 0
	s_setprio 1
	v_mfma_f32_16x16x32_bf16 v[118:121], v[166:169], v[182:185], v[118:121]
	v_mfma_f32_16x16x32_bf16 v[114:117], v[174:177], v[182:185], v[114:117]
	v_mfma_f32_16x16x32_bf16 v[102:105], v[166:169], v[190:193], v[102:105]
	v_mfma_f32_16x16x32_bf16 v[96:99], v[174:177], v[190:193], v[96:99]
	v_mfma_f32_16x16x32_bf16 v[84:87], v[166:169], v[198:201], v[84:87]
	v_mfma_f32_16x16x32_bf16 v[80:83], v[174:177], v[198:201], v[80:83]
	v_mfma_f32_16x16x32_bf16 v[68:71], v[166:169], v[208:211], v[68:71]
	v_mfma_f32_16x16x32_bf16 v[64:67], v[174:177], v[208:211], v[64:67]
	v_mfma_f32_16x16x32_bf16 v[118:121], v[170:173], v[186:189], v[118:121]
	v_mfma_f32_16x16x32_bf16 v[114:117], v[178:181], v[186:189], v[114:117]
	v_mfma_f32_16x16x32_bf16 v[102:105], v[170:173], v[194:197], v[102:105]
	v_mfma_f32_16x16x32_bf16 v[96:99], v[178:181], v[194:197], v[96:99]
	v_mfma_f32_16x16x32_bf16 v[84:87], v[170:173], v[202:205], v[84:87]
	v_mfma_f32_16x16x32_bf16 v[80:83], v[178:181], v[202:205], v[80:83]
	v_mfma_f32_16x16x32_bf16 v[68:71], v[170:173], v[226:229], v[68:71]
	v_mfma_f32_16x16x32_bf16 v[64:67], v[178:181], v[226:229], v[64:67]
	s_setprio 0
	s_barrier
	s_add_i32 s33, s33, s34
	v_lshl_add_u64 v[152:153], s[14:15], 0, v[132:133]
	s_mov_b32 m0, s33
	ds_read_b128 v[182:185], v156 offset:16384
	ds_read_b128 v[186:189], v156 offset:17408
	ds_read_b128 v[190:193], v156 offset:18432
	ds_read_b128 v[194:197], v156 offset:19456
	ds_read_b128 v[198:201], v156 offset:20480
	ds_read_b128 v[202:205], v156 offset:21504
	ds_read_b128 v[208:211], v156 offset:22528
	ds_read_b128 v[226:229], v156 offset:23552
	global_load_lds_dwordx4 v[152:153], off
	s_add_i32 m0, s33, 0x2000
	s_add_u32 s80, s14, 0x40000
	v_lshl_add_u64 v[212:213], s[14:15], 0, v[136:137]
	s_addc_u32 s81, s15, 0
	s_add_i32 s1, s1, s34
	global_load_lds_dwordx4 v[212:213], off
	v_lshl_add_u64 v[230:231], s[80:81], 0, v[132:133]
	s_mov_b32 m0, s1
	v_lshl_add_u64 v[232:233], s[28:29], 0, v[134:135]
	global_load_lds_dwordx4 v[230:231], off
	v_lshl_add_u64 v[230:231], s[80:81], 0, v[136:137]
	s_add_i32 m0, s1, 0x2000
	s_nop 0
	global_load_lds_dwordx4 v[230:231], off
	v_lshl_add_u64 v[230:231], s[28:29], 0, v[130:131]
	s_mov_b32 m0, s41
	s_nop 0
	global_load_lds_dwordx4 v[230:231], off
	s_mov_b32 m0, s60
	s_nop 0
	global_load_lds_dwordx4 v[232:233], off
	s_waitcnt vmcnt(8)
	s_waitcnt lgkmcnt(0)
	s_barrier
	s_setprio 1
	s_waitcnt lgkmcnt(0)
	v_mfma_f32_16x16x32_bf16 v[60:63], v[144:147], v[182:185], v[60:63]
	v_mfma_f32_16x16x32_bf16 v[56:59], v[158:161], v[182:185], v[56:59]
	v_mfma_f32_16x16x32_bf16 v[44:47], v[144:147], v[190:193], v[44:47]
	v_mfma_f32_16x16x32_bf16 v[40:43], v[158:161], v[190:193], v[40:43]
	v_mfma_f32_16x16x32_bf16 v[28:31], v[144:147], v[198:201], v[28:31]
	v_mfma_f32_16x16x32_bf16 v[24:27], v[158:161], v[198:201], v[24:27]
	v_mfma_f32_16x16x32_bf16 v[12:15], v[144:147], v[208:211], v[12:15]
	v_mfma_f32_16x16x32_bf16 v[8:11], v[158:161], v[208:211], v[8:11]
	v_mfma_f32_16x16x32_bf16 v[60:63], v[148:151], v[186:189], v[60:63]
	v_mfma_f32_16x16x32_bf16 v[56:59], v[162:165], v[186:189], v[56:59]
	v_mfma_f32_16x16x32_bf16 v[44:47], v[148:151], v[194:197], v[44:47]
	v_mfma_f32_16x16x32_bf16 v[40:43], v[162:165], v[194:197], v[40:43]
	v_mfma_f32_16x16x32_bf16 v[28:31], v[148:151], v[202:205], v[28:31]
	v_mfma_f32_16x16x32_bf16 v[24:27], v[162:165], v[202:205], v[24:27]
	v_mfma_f32_16x16x32_bf16 v[12:15], v[148:151], v[226:229], v[12:15]
	v_mfma_f32_16x16x32_bf16 v[8:11], v[162:165], v[226:229], v[8:11]
	s_setprio 0
	s_setprio 1
	v_mfma_f32_16x16x32_bf16 v[52:55], v[166:169], v[182:185], v[52:55]
	v_mfma_f32_16x16x32_bf16 v[48:51], v[174:177], v[182:185], v[48:51]
	v_mfma_f32_16x16x32_bf16 v[36:39], v[166:169], v[190:193], v[36:39]
	v_mfma_f32_16x16x32_bf16 v[32:35], v[174:177], v[190:193], v[32:35]
	v_mfma_f32_16x16x32_bf16 v[20:23], v[166:169], v[198:201], v[20:23]
	v_mfma_f32_16x16x32_bf16 v[16:19], v[174:177], v[198:201], v[16:19]
	v_mfma_f32_16x16x32_bf16 v[4:7], v[166:169], v[208:211], v[4:7]
	v_mfma_f32_16x16x32_bf16 v[0:3], v[174:177], v[208:211], v[0:3]
	v_mfma_f32_16x16x32_bf16 v[52:55], v[170:173], v[186:189], v[52:55]
	v_mfma_f32_16x16x32_bf16 v[48:51], v[178:181], v[186:189], v[48:51]
	v_mfma_f32_16x16x32_bf16 v[36:39], v[170:173], v[194:197], v[36:39]
	v_mfma_f32_16x16x32_bf16 v[32:35], v[178:181], v[194:197], v[32:35]
	v_mfma_f32_16x16x32_bf16 v[20:23], v[170:173], v[202:205], v[20:23]
	v_mfma_f32_16x16x32_bf16 v[16:19], v[178:181], v[202:205], v[16:19]
	v_mfma_f32_16x16x32_bf16 v[4:7], v[170:173], v[226:229], v[4:7]
	v_mfma_f32_16x16x32_bf16 v[0:3], v[178:181], v[226:229], v[0:3]
	s_setprio 0
	s_barrier
	s_add_i32 s1, 0, 0x18000
	v_add_u32_e32 v100, s1, v154
	s_add_i32 s33, 0, 0x1c000
	ds_read_b128 v[144:147], v100
	ds_read_b128 v[148:151], v100 offset:1024
	ds_read_b128 v[158:161], v100 offset:2048
	ds_read_b128 v[162:165], v100 offset:3072
	v_add_u32_e32 v100, s33, v154
	ds_read_b128 v[166:169], v100
	ds_read_b128 v[170:173], v100 offset:1024
	ds_read_b128 v[174:177], v100 offset:2048
	ds_read_b128 v[178:181], v100 offset:3072
	s_add_u32 s28, s28, 0x40000
	s_addc_u32 s29, s29, 0
	s_mov_b32 m0, s61
	v_lshl_add_u64 v[234:235], s[28:29], 0, v[130:131]
	ds_read_b128 v[182:185], v156 offset:32768
	ds_read_b128 v[186:189], v156 offset:33792
	ds_read_b128 v[190:193], v156 offset:34816
	ds_read_b128 v[194:197], v156 offset:35840
	ds_read_b128 v[198:201], v156 offset:36864
	ds_read_b128 v[202:205], v156 offset:37888
	ds_read_b128 v[208:211], v156 offset:38912
	ds_read_b128 v[226:229], v156 offset:39936
	global_load_lds_dwordx4 v[234:235], off
	v_lshl_add_u64 v[234:235], s[28:29], 0, v[134:135]
	s_mov_b32 m0, s69
	s_nop 0
	global_load_lds_dwordx4 v[234:235], off
	s_waitcnt vmcnt(8)
	s_waitcnt lgkmcnt(0)
	s_barrier
	s_setprio 1
	s_waitcnt lgkmcnt(0)
	v_mfma_f32_16x16x32_bf16 v[126:129], v[144:147], v[182:185], v[126:129]
	v_mfma_f32_16x16x32_bf16 v[122:125], v[158:161], v[182:185], v[122:125]
	v_mfma_f32_16x16x32_bf16 v[110:113], v[144:147], v[190:193], v[110:113]
	v_mfma_f32_16x16x32_bf16 v[106:109], v[158:161], v[190:193], v[106:109]
	v_mfma_f32_16x16x32_bf16 v[92:95], v[144:147], v[198:201], v[92:95]
	v_mfma_f32_16x16x32_bf16 v[88:91], v[158:161], v[198:201], v[88:91]
	v_mfma_f32_16x16x32_bf16 v[76:79], v[144:147], v[208:211], v[76:79]
	v_mfma_f32_16x16x32_bf16 v[72:75], v[158:161], v[208:211], v[72:75]
	v_mfma_f32_16x16x32_bf16 v[126:129], v[148:151], v[186:189], v[126:129]
	v_mfma_f32_16x16x32_bf16 v[122:125], v[162:165], v[186:189], v[122:125]
	v_mfma_f32_16x16x32_bf16 v[110:113], v[148:151], v[194:197], v[110:113]
	v_mfma_f32_16x16x32_bf16 v[106:109], v[162:165], v[194:197], v[106:109]
	v_mfma_f32_16x16x32_bf16 v[92:95], v[148:151], v[202:205], v[92:95]
	v_mfma_f32_16x16x32_bf16 v[88:91], v[162:165], v[202:205], v[88:91]
	v_mfma_f32_16x16x32_bf16 v[76:79], v[148:151], v[226:229], v[76:79]
	v_mfma_f32_16x16x32_bf16 v[72:75], v[162:165], v[226:229], v[72:75]
	s_setprio 0
	s_setprio 1
	v_mfma_f32_16x16x32_bf16 v[118:121], v[166:169], v[182:185], v[118:121]
	v_mfma_f32_16x16x32_bf16 v[114:117], v[174:177], v[182:185], v[114:117]
	v_mfma_f32_16x16x32_bf16 v[102:105], v[166:169], v[190:193], v[102:105]
	v_mfma_f32_16x16x32_bf16 v[96:99], v[174:177], v[190:193], v[96:99]
	v_mfma_f32_16x16x32_bf16 v[84:87], v[166:169], v[198:201], v[84:87]
	v_mfma_f32_16x16x32_bf16 v[80:83], v[174:177], v[198:201], v[80:83]
	v_mfma_f32_16x16x32_bf16 v[68:71], v[166:169], v[208:211], v[68:71]
	v_mfma_f32_16x16x32_bf16 v[64:67], v[174:177], v[208:211], v[64:67]
	v_mfma_f32_16x16x32_bf16 v[118:121], v[170:173], v[186:189], v[118:121]
	v_mfma_f32_16x16x32_bf16 v[114:117], v[178:181], v[186:189], v[114:117]
	v_mfma_f32_16x16x32_bf16 v[102:105], v[170:173], v[194:197], v[102:105]
	v_mfma_f32_16x16x32_bf16 v[96:99], v[178:181], v[194:197], v[96:99]
	v_mfma_f32_16x16x32_bf16 v[84:87], v[170:173], v[202:205], v[84:87]
	v_mfma_f32_16x16x32_bf16 v[80:83], v[178:181], v[202:205], v[80:83]
	v_mfma_f32_16x16x32_bf16 v[68:71], v[170:173], v[226:229], v[68:71]
	v_mfma_f32_16x16x32_bf16 v[64:67], v[178:181], v[226:229], v[64:67]
	s_setprio 0
	s_barrier
	s_add_i32 s1, s1, s34
	v_lshl_add_u64 v[152:153], v[152:153], 0, s[86:87]
	s_mov_b32 m0, s1
	ds_read_b128 v[182:185], v156 offset:49152
	ds_read_b128 v[186:189], v156 offset:50176
	ds_read_b128 v[190:193], v156 offset:51200
	ds_read_b128 v[194:197], v156 offset:52224
	ds_read_b128 v[198:201], v156 offset:53248
	ds_read_b128 v[202:205], v156 offset:54272
	ds_read_b128 v[208:211], v156 offset:55296
	ds_read_b128 v[226:229], v156 offset:56320
	global_load_lds_dwordx4 v[152:153], off
	s_add_i32 m0, s1, 0x2000
	s_add_u32 s14, s14, 0x40080
	v_lshl_add_u64 v[152:153], v[212:213], 0, s[86:87]
	s_addc_u32 s15, s15, 0
	s_add_i32 s1, s33, s34
	global_load_lds_dwordx4 v[152:153], off
	v_lshl_add_u64 v[152:153], s[14:15], 0, v[132:133]
	s_mov_b32 m0, s1
	s_nop 0
	global_load_lds_dwordx4 v[152:153], off
	v_lshl_add_u64 v[152:153], s[14:15], 0, v[136:137]
	s_add_i32 m0, s1, 0x2000
	s_nop 0
	global_load_lds_dwordx4 v[152:153], off
	v_lshl_add_u64 v[152:153], v[230:231], 0, s[86:87]
	s_mov_b32 m0, s89
	s_nop 0
	global_load_lds_dwordx4 v[152:153], off
	v_lshl_add_u64 v[152:153], v[232:233], 0, s[86:87]
	s_mov_b32 m0, s92
	s_nop 0
	global_load_lds_dwordx4 v[152:153], off
	s_waitcnt vmcnt(8)
	s_waitcnt lgkmcnt(0)
	s_barrier
	s_setprio 1
	s_waitcnt lgkmcnt(0)
	v_mfma_f32_16x16x32_bf16 v[60:63], v[144:147], v[182:185], v[60:63]
	v_and_b32_e32 v100, 3, v224
	v_lshlrev_b32_e32 v100, 6, v100
	v_and_or_b32 v100, v224, 60, v100
	v_mov_b32_e32 v234, v247
	v_fmamk_f32 v235, v236, 0x3a800000, v207
	v_mfma_f32_16x16x32_bf16 v[56:59], v[158:161], v[182:185], v[56:59]
	v_rsq_f32_e32 v235, v235
	s_nop 0
	v_mul_f32_e32 v235, s36, v235
	v_mul_f32_e32 v126, v235, v126
	v_mul_f32_e32 v127, v235, v127
	v_mul_f32_e32 v128, v235, v128
	v_mfma_f32_16x16x32_bf16 v[44:47], v[144:147], v[190:193], v[44:47]
	v_mul_f32_e32 v129, v235, v129
	v_mul_f32_e32 v122, v235, v122
	v_mul_f32_e32 v123, v235, v123
	v_mul_f32_e32 v124, v235, v124
	v_mul_f32_e32 v125, v235, v125
	v_cvt_pk_bf16_f32 v126, v126, v127
	v_mfma_f32_16x16x32_bf16 v[40:43], v[158:161], v[190:193], v[40:43]
	v_cvt_pk_bf16_f32 v127, v128, v129
	v_cvt_pk_bf16_f32 v128, v122, v123
	v_cvt_pk_bf16_f32 v129, v124, v125
	ds_bpermute_b32 v122, v100, v126
	ds_bpermute_b32 v123, v100, v127
	ds_bpermute_b32 v124, v100, v128
	v_mfma_f32_16x16x32_bf16 v[28:31], v[144:147], v[198:201], v[28:31]
	ds_bpermute_b32 v125, v100, v129
	v_fmamk_f32 v235, v237, 0x3a800000, v207
	v_rsq_f32_e32 v235, v235
	s_nop 0
	v_mul_f32_e32 v235, s36, v235
	v_mul_f32_e32 v110, v235, v110
	v_mfma_f32_16x16x32_bf16 v[24:27], v[158:161], v[198:201], v[24:27]
	v_mul_f32_e32 v111, v235, v111
	v_mul_f32_e32 v112, v235, v112
	v_mul_f32_e32 v113, v235, v113
	v_mul_f32_e32 v106, v235, v106
	v_mul_f32_e32 v107, v235, v107
	v_mul_f32_e32 v108, v235, v108
	v_mfma_f32_16x16x32_bf16 v[12:15], v[144:147], v[208:211], v[12:15]
	v_mul_f32_e32 v109, v235, v109
	v_cvt_pk_bf16_f32 v110, v110, v111
	v_cvt_pk_bf16_f32 v111, v112, v113
	v_cvt_pk_bf16_f32 v112, v106, v107
	v_cvt_pk_bf16_f32 v113, v108, v109
	ds_bpermute_b32 v106, v100, v110
	v_mfma_f32_16x16x32_bf16 v[8:11], v[158:161], v[208:211], v[8:11]
	ds_bpermute_b32 v107, v100, v111
	ds_bpermute_b32 v108, v100, v112
	ds_bpermute_b32 v109, v100, v113
	s_waitcnt lgkmcnt(4)
	global_store_dwordx4 v234, v[122:125], s[2:3] nt
	v_add_u32_e32 v234, s0, v234
	v_mfma_f32_16x16x32_bf16 v[60:63], v[148:151], v[186:189], v[60:63]
	v_fmamk_f32 v235, v238, 0x3a800000, v207
	v_rsq_f32_e32 v235, v235
	s_nop 0
	v_mul_f32_e32 v235, s36, v235
	v_mul_f32_e32 v92, v235, v92
	v_mul_f32_e32 v93, v235, v93
	v_mfma_f32_16x16x32_bf16 v[56:59], v[162:165], v[186:189], v[56:59]
	v_mul_f32_e32 v94, v235, v94
	v_mul_f32_e32 v95, v235, v95
	v_mul_f32_e32 v88, v235, v88
	v_mul_f32_e32 v89, v235, v89
	v_mul_f32_e32 v90, v235, v90
	v_mul_f32_e32 v91, v235, v91
	v_mfma_f32_16x16x32_bf16 v[44:47], v[148:151], v[194:197], v[44:47]
	v_cvt_pk_bf16_f32 v92, v92, v93
	v_cvt_pk_bf16_f32 v93, v94, v95
	v_cvt_pk_bf16_f32 v94, v88, v89
	v_cvt_pk_bf16_f32 v95, v90, v91
	ds_bpermute_b32 v88, v100, v92
	ds_bpermute_b32 v89, v100, v93
	v_mfma_f32_16x16x32_bf16 v[40:43], v[162:165], v[194:197], v[40:43]
	ds_bpermute_b32 v90, v100, v94
	ds_bpermute_b32 v91, v100, v95
	s_waitcnt lgkmcnt(4)
	global_store_dwordx4 v234, v[106:109], s[2:3] nt
	v_add_u32_e32 v234, s0, v234
	v_fmamk_f32 v235, v239, 0x3a800000, v207
	v_mfma_f32_16x16x32_bf16 v[28:31], v[148:151], v[202:205], v[28:31]
	v_rsq_f32_e32 v235, v235
	s_nop 0
	v_mul_f32_e32 v235, s36, v235
	v_mul_f32_e32 v76, v235, v76
	v_mul_f32_e32 v77, v235, v77
	v_mul_f32_e32 v78, v235, v78
	v_mfma_f32_16x16x32_bf16 v[24:27], v[162:165], v[202:205], v[24:27]
	v_mul_f32_e32 v79, v235, v79
	v_mul_f32_e32 v72, v235, v72
	v_mul_f32_e32 v73, v235, v73
	v_mul_f32_e32 v74, v235, v74
	v_mul_f32_e32 v75, v235, v75
	v_cvt_pk_bf16_f32 v76, v76, v77
	v_mfma_f32_16x16x32_bf16 v[12:15], v[148:151], v[226:229], v[12:15]
	v_cvt_pk_bf16_f32 v77, v78, v79
	v_cvt_pk_bf16_f32 v78, v72, v73
	v_cvt_pk_bf16_f32 v79, v74, v75
	ds_bpermute_b32 v72, v100, v76
	ds_bpermute_b32 v73, v100, v77
	ds_bpermute_b32 v74, v100, v78
	v_mfma_f32_16x16x32_bf16 v[8:11], v[162:165], v[226:229], v[8:11]
	ds_bpermute_b32 v75, v100, v79
	s_waitcnt lgkmcnt(4)
	global_store_dwordx4 v234, v[88:91], s[2:3] nt
	v_add_u32_e32 v234, s0, v234
	s_waitcnt lgkmcnt(0)
	global_store_dwordx4 v234, v[72:75], s[2:3] nt
	s_setprio 0
	s_setprio 1
	v_mfma_f32_16x16x32_bf16 v[52:55], v[166:169], v[182:185], v[52:55]
	v_add_u32_e32 v234, s32, v247
	v_fmamk_f32 v235, v236, 0x3a800000, v207
	v_rsq_f32_e32 v235, v235
	s_nop 0
	v_mul_f32_e32 v235, s36, v235
	v_mfma_f32_16x16x32_bf16 v[48:51], v[174:177], v[182:185], v[48:51]
	v_mul_f32_e32 v118, v235, v118
	v_mul_f32_e32 v119, v235, v119
	v_mul_f32_e32 v120, v235, v120
	v_mul_f32_e32 v121, v235, v121
	v_mul_f32_e32 v114, v235, v114
	v_mul_f32_e32 v115, v235, v115
	v_mfma_f32_16x16x32_bf16 v[36:39], v[166:169], v[190:193], v[36:39]
	v_mul_f32_e32 v116, v235, v116
	v_mul_f32_e32 v117, v235, v117
	v_cvt_pk_bf16_f32 v118, v118, v119
	v_cvt_pk_bf16_f32 v119, v120, v121
	v_cvt_pk_bf16_f32 v120, v114, v115
	v_cvt_pk_bf16_f32 v121, v116, v117
	v_mfma_f32_16x16x32_bf16 v[32:35], v[174:177], v[190:193], v[32:35]
	ds_bpermute_b32 v114, v100, v118
	ds_bpermute_b32 v115, v100, v119
	ds_bpermute_b32 v116, v100, v120
	ds_bpermute_b32 v117, v100, v121
	v_fmamk_f32 v235, v237, 0x3a800000, v207
	v_rsq_f32_e32 v235, v235
	v_mfma_f32_16x16x32_bf16 v[20:23], v[166:169], v[198:201], v[20:23]
	s_nop 0
	v_mul_f32_e32 v235, s36, v235
	v_mul_f32_e32 v102, v235, v102
	v_mul_f32_e32 v103, v235, v103
	v_mul_f32_e32 v104, v235, v104
	v_mfma_f32_16x16x32_bf16 v[16:19], v[174:177], v[198:201], v[16:19]
	v_mul_f32_e32 v105, v235, v105
	v_mul_f32_e32 v96, v235, v96
	v_mul_f32_e32 v97, v235, v97
	v_mul_f32_e32 v98, v235, v98
	v_mul_f32_e32 v99, v235, v99
	v_cvt_pk_bf16_f32 v102, v102, v103
	v_mfma_f32_16x16x32_bf16 v[4:7], v[166:169], v[208:211], v[4:7]
	v_cvt_pk_bf16_f32 v103, v104, v105
	v_cvt_pk_bf16_f32 v104, v96, v97
	v_cvt_pk_bf16_f32 v105, v98, v99
	ds_bpermute_b32 v96, v100, v102
	ds_bpermute_b32 v97, v100, v103
	ds_bpermute_b32 v98, v100, v104
	v_mfma_f32_16x16x32_bf16 v[0:3], v[174:177], v[208:211], v[0:3]
	ds_bpermute_b32 v99, v100, v105
	s_waitcnt lgkmcnt(4)
	global_store_dwordx4 v234, v[114:117], s[2:3] nt
	v_add_u32_e32 v234, s0, v234
	v_fmamk_f32 v235, v238, 0x3a800000, v207
	v_rsq_f32_e32 v235, v235
	v_mfma_f32_16x16x32_bf16 v[52:55], v[170:173], v[186:189], v[52:55]
	s_nop 0
	v_mul_f32_e32 v235, s36, v235
	v_mul_f32_e32 v84, v235, v84
	v_mul_f32_e32 v85, v235, v85
	v_mul_f32_e32 v86, v235, v86
	v_mfma_f32_16x16x32_bf16 v[48:51], v[178:181], v[186:189], v[48:51]
	v_mul_f32_e32 v87, v235, v87
	v_mul_f32_e32 v80, v235, v80
	v_mul_f32_e32 v81, v235, v81
	v_mul_f32_e32 v82, v235, v82
	v_mul_f32_e32 v83, v235, v83
	v_cvt_pk_bf16_f32 v84, v84, v85
	v_mfma_f32_16x16x32_bf16 v[36:39], v[170:173], v[194:197], v[36:39]
	v_cvt_pk_bf16_f32 v85, v86, v87
	v_cvt_pk_bf16_f32 v86, v80, v81
	v_cvt_pk_bf16_f32 v87, v82, v83
	ds_bpermute_b32 v80, v100, v84
	ds_bpermute_b32 v81, v100, v85
	ds_bpermute_b32 v82, v100, v86
	v_mfma_f32_16x16x32_bf16 v[32:35], v[178:181], v[194:197], v[32:35]
	ds_bpermute_b32 v83, v100, v87
	s_waitcnt lgkmcnt(4)
	global_store_dwordx4 v234, v[96:99], s[2:3] nt
	v_add_u32_e32 v234, s0, v234
	v_fmamk_f32 v235, v239, 0x3a800000, v207
	v_rsq_f32_e32 v235, v235
	v_mfma_f32_16x16x32_bf16 v[20:23], v[170:173], v[202:205], v[20:23]
	s_nop 0
	v_mul_f32_e32 v235, s36, v235
	v_mul_f32_e32 v68, v235, v68
	v_mul_f32_e32 v69, v235, v69
	v_mul_f32_e32 v70, v235, v70
	v_mfma_f32_16x16x32_bf16 v[16:19], v[178:181], v[202:205], v[16:19]
	v_mul_f32_e32 v71, v235, v71
	v_mul_f32_e32 v64, v235, v64
	v_mul_f32_e32 v65, v235, v65
	v_mul_f32_e32 v66, v235, v66
	v_mul_f32_e32 v67, v235, v67
	v_cvt_pk_bf16_f32 v68, v68, v69
	v_mfma_f32_16x16x32_bf16 v[4:7], v[170:173], v[226:229], v[4:7]
	v_cvt_pk_bf16_f32 v69, v70, v71
	v_cvt_pk_bf16_f32 v70, v64, v65
	v_cvt_pk_bf16_f32 v71, v66, v67
	ds_bpermute_b32 v64, v100, v68
	ds_bpermute_b32 v65, v100, v69
	ds_bpermute_b32 v66, v100, v70
	v_mfma_f32_16x16x32_bf16 v[0:3], v[178:181], v[226:229], v[0:3]
	ds_bpermute_b32 v67, v100, v71
	s_waitcnt lgkmcnt(4)
	global_store_dwordx4 v234, v[80:83], s[2:3] nt
	v_add_u32_e32 v234, s0, v234
	s_waitcnt lgkmcnt(0)
	global_store_dwordx4 v234, v[64:67], s[2:3] nt
	s_setprio 0
	s_barrier
	s_add_i32 s73, s73, 2
	s_add_u32 s12, s12, 0x100
	s_addc_u32 s13, s13, 0
	s_add_u32 s54, s54, 0x100
	s_addc_u32 s55, s55, 0
	s_mov_b32 s37, 1
	s_branch .LBB0_391

.LBB0_401:
	s_cmp_lt_i32 s47, 2
	s_cselect_b64 s[30:31], -1, 0
	s_and_b64 s[30:31], s[30:31], s[64:65]
.Lmy_b16_inplace:
	s_mov_b32 s37, 0
	s_and_b64 vcc, exec, s[70:71]
	s_cbranch_vccz .Lmy_b16_inplace2
	s_barrier
